# K-loops: MFMA blocks at priority 2, load segments at 1, windows at 0, so the loading partner wins the windows regardless of wave age
# speedup vs baseline: 1.0030x; 1.0030x over previous
; #define PG8_STAGE(bufoff, gbase, voff) do { _Pragma("unroll") for (int _i = 0; _i < 2; ++_i) \
;         __builtin_amdgcn_global_load_lds((const unsigned*)((const char*)(gbase) + (voff)[_i]), (PG8_LAS unsigned*)(lds + (bufoff) + ldsw + _i * 8192), 16, 0, 0); } while (0)
; #define PG8_LDA(dst, b, h) do { _Pragma("unroll") for (int m = 0; m < 4; ++m) _Pragma("unroll") for (int k = 0; k < 2; ++k) dst[m][k] = *(const PG8_LAS bf16x8*)(lds + PG8_SA(b, h) + aoff + m * 2048 + k * 1024); } while (0)
; #define PG8_LDB(dst, b, h) do { _Pragma("unroll") for (int n = 0; n < 2; ++n) _Pragma("unroll") for (int k = 0; k < 2; ++k) dst[n][k] = *(const PG8_LAS bf16x8*)(lds + PG8_SB(b, h) + boff + n * 2048 + k * 1024); } while (0)
; #define PG8_MMA(ai, bj, At, Bt) do { __builtin_amdgcn_s_setprio(1); _Pragma("unroll") for (int m = 0; m < 4; ++m) _Pragma("unroll") for (int n = 0; n < 2; ++n) _Pragma("unroll") for (int k = 0; k < 2; ++k) \
;         acc[ai][bj][m][n] = __builtin_amdgcn_mfma_f32_16x16x32_bf16(Bt[n][k], At[m][k], acc[ai][bj][m][n], 0, 0, 0); __builtin_amdgcn_s_setprio(0); } while (0)
; #define PG8_WAIT_V(n) asm volatile("s_waitcnt vmcnt(" #n ")" ::: "memory")
; #define PG8_BAR __builtin_amdgcn_s_barrier()
; template <class Epi, class Sched, bool ALIGN_EPI = false, bool SP2 = false>
; __device__ __forceinline__ void gemm_phase(PG8_LAS unsigned char* lds, const Gemm g, const Sched& S, const Epi& E) {
;     ...
;         for (int t = 0; t < nt; t += 2) {
;             const bool last = (t == nt - 2);
;             const char* a1 = cA + (size_t)(t + 1) * kstep;
;             const char* a2 = last ? nA : cA + (size_t)(t + 2) * kstep; const char* b2 = last ? nB : cB + (size_t)(t + 2) * kstep;
;             const char* a3 = a2 + kstep; const char* b3 = b2 + kstep;
;             if (last && has_next) S.a_ready(nxt);
;             if constexpr (SP2) {
;             PG8_LDB(B0, 0, 0); PG8_LDB(B1, 0, 1); PG8_SCHED; PG8_LDA(At, 0, 0); PG8_STAGE(PG8_SA(1, 1), a1 + hstep, voffA);
;             PG8_WAIT_V(8); PG8_WAIT_L(0); PG8_BAR; PG8_MMA(0, 0, At, B0); PG8_MMA(0, 1, At, B1); PG8_BAR; PG8_SCHED;
;             PG8_LDA(At, 0, 1); PG8_STAGE(PG8_SB(0, 0), b2, voffB); PG8_STAGE(PG8_SB(0, 1), b2 + hstep, voffB); PG8_STAGE(PG8_SA(0, 0), a2, voffA);
;             PG8_WAIT_V(8); PG8_WAIT_L(0); PG8_BAR; PG8_MMA(1, 0, At, B0); PG8_MMA(1, 1, At, B1); PG8_BAR; PG8_SCHED;
.LBB0_36:
	s_add_u32 s18, s58, 0xffe00080
	s_addc_u32 s19, s59, -1
	s_add_i32 s47, 0, 0x10000
	s_cmpk_eq_i32 s46, 0x7c
	s_cselect_b32 s63, s45, s19
	s_cselect_b32 s62, s73, s18
	v_add_u32_e32 v160, s47, v143
	s_cselect_b32 s19, s37, s79
	s_cselect_b32 s18, s84, s78
	s_add_i32 s80, 0, 0x14000
	ds_read_b128 v[156:159], v160
	ds_read_b128 v[164:167], v160 offset:1024
	ds_read_b128 v[168:171], v160 offset:2048
	ds_read_b128 v[172:175], v160 offset:3072
	v_add_u32_e32 v160, s80, v143
	ds_read_b128 v[176:179], v160
	ds_read_b128 v[180:183], v160 offset:1024
	ds_read_b128 v[184:187], v160 offset:2048
	ds_read_b128 v[204:207], v160 offset:3072
	v_lshl_add_u64 v[160:161], s[58:59], 0, v[152:153]
	s_add_i32 m0, s5, 0xc000
	ds_read_b128 v[208:211], v163
	ds_read_b128 v[212:215], v163 offset:1024
	ds_read_b128 v[216:219], v163 offset:2048
	ds_read_b128 v[220:223], v163 offset:3072
	ds_read_b128 v[224:227], v163 offset:4096
	ds_read_b128 v[228:231], v163 offset:5120
	ds_read_b128 v[232:235], v163 offset:6144
	ds_read_b128 v[236:239], v163 offset:7168
	global_load_lds_dwordx4 v[160:161], off
	v_lshl_add_u64 v[160:161], s[58:59], 0, v[154:155]
	s_add_i32 m0, s5, 0xe000
	s_nop 0
	global_load_lds_dwordx4 v[160:161], off
	s_nop 0
	s_waitcnt vmcnt(8)
	s_waitcnt lgkmcnt(0)
	s_barrier
	s_setprio 2
	v_mfma_f32_16x16x32_bf16 v[126:129], v[156:159], v[208:211], v[126:129]
	v_mfma_f32_16x16x32_bf16 v[122:125], v[168:171], v[208:211], v[122:125]
	v_mfma_f32_16x16x32_bf16 v[110:113], v[156:159], v[216:219], v[110:113]
	v_mfma_f32_16x16x32_bf16 v[106:109], v[168:171], v[216:219], v[106:109]
	v_mfma_f32_16x16x32_bf16 v[94:97], v[156:159], v[224:227], v[94:97]
	v_mfma_f32_16x16x32_bf16 v[90:93], v[168:171], v[224:227], v[90:93]
	v_mfma_f32_16x16x32_bf16 v[78:81], v[156:159], v[232:235], v[78:81]
	v_mfma_f32_16x16x32_bf16 v[74:77], v[168:171], v[232:235], v[74:77]
	s_setprio 0
	s_setprio 2
	v_mfma_f32_16x16x32_bf16 v[126:129], v[164:167], v[212:215], v[126:129]
	v_mfma_f32_16x16x32_bf16 v[122:125], v[172:175], v[212:215], v[122:125]
	v_mfma_f32_16x16x32_bf16 v[110:113], v[164:167], v[220:223], v[110:113]
	v_mfma_f32_16x16x32_bf16 v[106:109], v[172:175], v[220:223], v[106:109]
	v_mfma_f32_16x16x32_bf16 v[94:97], v[164:167], v[228:231], v[94:97]
	v_mfma_f32_16x16x32_bf16 v[90:93], v[172:175], v[228:231], v[90:93]
	v_mfma_f32_16x16x32_bf16 v[78:81], v[164:167], v[236:239], v[78:81]
	v_mfma_f32_16x16x32_bf16 v[74:77], v[172:175], v[236:239], v[74:77]
	s_setprio 0
	s_setprio 2
	v_mfma_f32_16x16x32_bf16 v[118:121], v[176:179], v[208:211], v[118:121]
	v_mfma_f32_16x16x32_bf16 v[114:117], v[184:187], v[208:211], v[114:117]
	v_mfma_f32_16x16x32_bf16 v[102:105], v[176:179], v[216:219], v[102:105]
	v_mfma_f32_16x16x32_bf16 v[98:101], v[184:187], v[216:219], v[98:101]
	v_mfma_f32_16x16x32_bf16 v[86:89], v[176:179], v[224:227], v[86:89]
	v_mfma_f32_16x16x32_bf16 v[82:85], v[184:187], v[224:227], v[82:85]
	v_mfma_f32_16x16x32_bf16 v[70:73], v[176:179], v[232:235], v[70:73]
	v_mfma_f32_16x16x32_bf16 v[66:69], v[184:187], v[232:235], v[66:69]
	s_setprio 0
	s_setprio 2
	v_mfma_f32_16x16x32_bf16 v[118:121], v[180:183], v[212:215], v[118:121]
	v_mfma_f32_16x16x32_bf16 v[114:117], v[204:207], v[212:215], v[114:117]
	v_mfma_f32_16x16x32_bf16 v[102:105], v[180:183], v[220:223], v[102:105]
	v_mfma_f32_16x16x32_bf16 v[98:101], v[204:207], v[220:223], v[98:101]
	v_mfma_f32_16x16x32_bf16 v[86:89], v[180:183], v[228:231], v[86:89]
	v_mfma_f32_16x16x32_bf16 v[82:85], v[204:207], v[228:231], v[82:85]
	v_mfma_f32_16x16x32_bf16 v[70:73], v[180:183], v[236:239], v[70:73]
	v_mfma_f32_16x16x32_bf16 v[66:69], v[204:207], v[236:239], v[66:69]
	s_setprio 1
	s_barrier
	s_add_i32 s47, s47, s4
	v_lshl_add_u64 v[160:161], s[18:19], 0, v[148:149]
	s_mov_b32 m0, s47
	ds_read_b128 v[208:211], v163 offset:16384
	ds_read_b128 v[212:215], v163 offset:17408
	ds_read_b128 v[216:219], v163 offset:18432
	ds_read_b128 v[220:223], v163 offset:19456
	ds_read_b128 v[224:227], v163 offset:20480
	ds_read_b128 v[228:231], v163 offset:21504
	ds_read_b128 v[232:235], v163 offset:22528
	ds_read_b128 v[236:239], v163 offset:23552
	global_load_lds_dwordx4 v[160:161], off
	s_add_i32 m0, s47, 0x2000
	s_add_u32 s76, s18, 0x200000
	v_lshl_add_u64 v[240:241], s[18:19], 0, v[144:145]
	s_addc_u32 s77, s19, 0
	s_add_i32 s47, s80, s4
	global_load_lds_dwordx4 v[240:241], off
	v_lshl_add_u64 v[242:243], s[76:77], 0, v[148:149]
	s_mov_b32 m0, s47
	v_lshl_add_u64 v[244:245], s[62:63], 0, v[146:147]
	global_load_lds_dwordx4 v[242:243], off
	v_lshl_add_u64 v[242:243], s[76:77], 0, v[144:145]
	s_add_i32 m0, s47, 0x2000
	s_nop 0
	global_load_lds_dwordx4 v[242:243], off
	v_lshl_add_u64 v[242:243], s[62:63], 0, v[150:151]
	s_mov_b32 m0, s5
	s_nop 0
	global_load_lds_dwordx4 v[242:243], off
	s_mov_b32 m0, s30
	s_nop 0
	global_load_lds_dwordx4 v[244:245], off
	s_waitcnt vmcnt(8)
	s_waitcnt lgkmcnt(0)
	s_barrier
; #define PG8_STAGE(bufoff, gbase, voff) do { _Pragma("unroll") for (int _i = 0; _i < 2; ++_i) \
;         __builtin_amdgcn_global_load_lds((const unsigned*)((const char*)(gbase) + (voff)[_i]), (PG8_LAS unsigned*)(lds + (bufoff) + ldsw + _i * 8192), 16, 0, 0); } while (0)
; #define PG8_LDA(dst, b, h) do { _Pragma("unroll") for (int m = 0; m < 4; ++m) _Pragma("unroll") for (int k = 0; k < 2; ++k) dst[m][k] = *(const PG8_LAS bf16x8*)(lds + PG8_SA(b, h) + aoff + m * 2048 + k * 1024); } while (0)
; #define PG8_LDB(dst, b, h) do { _Pragma("unroll") for (int n = 0; n < 2; ++n) _Pragma("unroll") for (int k = 0; k < 2; ++k) dst[n][k] = *(const PG8_LAS bf16x8*)(lds + PG8_SB(b, h) + boff + n * 2048 + k * 1024); } while (0)
; #define PG8_MMA(ai, bj, At, Bt) do { __builtin_amdgcn_s_setprio(1); _Pragma("unroll") for (int m = 0; m < 4; ++m) _Pragma("unroll") for (int n = 0; n < 2; ++n) _Pragma("unroll") for (int k = 0; k < 2; ++k) \
;         acc[ai][bj][m][n] = __builtin_amdgcn_mfma_f32_16x16x32_bf16(Bt[n][k], At[m][k], acc[ai][bj][m][n], 0, 0, 0); __builtin_amdgcn_s_setprio(0); } while (0)
; #define PG8_WAIT_V(n) asm volatile("s_waitcnt vmcnt(" #n ")" ::: "memory")
; #define PG8_WAIT_L(n) asm volatile("s_waitcnt lgkmcnt(" #n ")" ::: "memory")
; #define PG8_BAR __builtin_amdgcn_s_barrier()
; #define PG8_SCHED __builtin_amdgcn_sched_barrier(0)
; template <class Epi, class Sched, bool ALIGN_EPI = false, bool SP2 = false>
; __device__ __forceinline__ void gemm_phase(PG8_LAS unsigned char* lds, const Gemm g, const Sched& S, const Epi& E) {
;     ...
;             PG8_WAIT_V(8); PG8_WAIT_L(0); PG8_BAR; PG8_MMA(1, 0, At, B0); PG8_MMA(1, 1, At, B1); PG8_BAR; PG8_SCHED;
;             PG8_LDB(B0, 1, 0); PG8_LDB(B1, 1, 1); PG8_SCHED; PG8_LDA(At, 1, 0); PG8_STAGE(PG8_SA(0, 1), a2 + hstep, voffA);
;             PG8_WAIT_V(8); PG8_WAIT_L(0); PG8_BAR; PG8_MMA(0, 0, At, B0); PG8_MMA(0, 1, At, B1); PG8_BAR; PG8_SCHED;
	s_setprio 2
	v_mfma_f32_16x16x32_bf16 v[62:65], v[156:159], v[208:211], v[62:65]
	v_mfma_f32_16x16x32_bf16 v[58:61], v[168:171], v[208:211], v[58:61]
	v_mfma_f32_16x16x32_bf16 v[46:49], v[156:159], v[216:219], v[46:49]
	v_mfma_f32_16x16x32_bf16 v[42:45], v[168:171], v[216:219], v[42:45]
	v_mfma_f32_16x16x32_bf16 v[30:33], v[156:159], v[224:227], v[30:33]
	v_mfma_f32_16x16x32_bf16 v[26:29], v[168:171], v[224:227], v[26:29]
	v_mfma_f32_16x16x32_bf16 v[14:17], v[156:159], v[232:235], v[14:17]
	v_mfma_f32_16x16x32_bf16 v[10:13], v[168:171], v[232:235], v[10:13]
	s_setprio 0
	s_setprio 2
	v_mfma_f32_16x16x32_bf16 v[62:65], v[164:167], v[212:215], v[62:65]
	v_mfma_f32_16x16x32_bf16 v[58:61], v[172:175], v[212:215], v[58:61]
	v_mfma_f32_16x16x32_bf16 v[46:49], v[164:167], v[220:223], v[46:49]
	v_mfma_f32_16x16x32_bf16 v[42:45], v[172:175], v[220:223], v[42:45]
	v_mfma_f32_16x16x32_bf16 v[30:33], v[164:167], v[228:231], v[30:33]
	v_mfma_f32_16x16x32_bf16 v[26:29], v[172:175], v[228:231], v[26:29]
	v_mfma_f32_16x16x32_bf16 v[14:17], v[164:167], v[236:239], v[14:17]
	v_mfma_f32_16x16x32_bf16 v[10:13], v[172:175], v[236:239], v[10:13]
	s_setprio 0
	s_setprio 2
	v_mfma_f32_16x16x32_bf16 v[54:57], v[176:179], v[208:211], v[54:57]
	v_mfma_f32_16x16x32_bf16 v[50:53], v[184:187], v[208:211], v[50:53]
	v_mfma_f32_16x16x32_bf16 v[38:41], v[176:179], v[216:219], v[38:41]
	v_mfma_f32_16x16x32_bf16 v[34:37], v[184:187], v[216:219], v[34:37]
	v_mfma_f32_16x16x32_bf16 v[22:25], v[176:179], v[224:227], v[22:25]
	v_mfma_f32_16x16x32_bf16 v[18:21], v[184:187], v[224:227], v[18:21]
	v_mfma_f32_16x16x32_bf16 v[6:9], v[176:179], v[232:235], v[6:9]
	v_mfma_f32_16x16x32_bf16 v[2:5], v[184:187], v[232:235], v[2:5]
	s_setprio 0
	s_setprio 2
	v_mfma_f32_16x16x32_bf16 v[54:57], v[180:183], v[212:215], v[54:57]
	v_mfma_f32_16x16x32_bf16 v[50:53], v[204:207], v[212:215], v[50:53]
	v_mfma_f32_16x16x32_bf16 v[38:41], v[180:183], v[220:223], v[38:41]
	v_mfma_f32_16x16x32_bf16 v[34:37], v[204:207], v[220:223], v[34:37]
	v_mfma_f32_16x16x32_bf16 v[22:25], v[180:183], v[228:231], v[22:25]
	v_mfma_f32_16x16x32_bf16 v[18:21], v[204:207], v[228:231], v[18:21]
	v_mfma_f32_16x16x32_bf16 v[6:9], v[180:183], v[236:239], v[6:9]
	v_mfma_f32_16x16x32_bf16 v[2:5], v[204:207], v[236:239], v[2:5]
	s_setprio 1
	s_barrier
	s_add_i32 s47, 0, 0x18000
	s_add_i32 s76, 0, 0x1c000
	v_add_u32_e32 v172, s47, v143
	v_add_u32_e32 v203, s76, v143
	ds_read_b128 v[156:159], v172
	ds_read_b128 v[164:167], v172 offset:1024
	ds_read_b128 v[168:171], v172 offset:2048
	ds_read_b128 v[172:175], v172 offset:3072
	ds_read_b128 v[176:179], v203
	ds_read_b128 v[180:183], v203 offset:1024
	ds_read_b128 v[184:187], v203 offset:2048
	ds_read_b128 v[204:207], v203 offset:3072
	s_add_u32 s62, s62, 0x200000
	s_addc_u32 s63, s63, 0
	s_mov_b32 m0, s57
	v_lshl_add_u64 v[246:247], s[62:63], 0, v[150:151]
	ds_read_b128 v[208:211], v163 offset:32768
	ds_read_b128 v[212:215], v163 offset:33792
	ds_read_b128 v[216:219], v163 offset:34816
	ds_read_b128 v[220:223], v163 offset:35840
	ds_read_b128 v[224:227], v163 offset:36864
	ds_read_b128 v[228:231], v163 offset:37888
	ds_read_b128 v[232:235], v163 offset:38912
	ds_read_b128 v[236:239], v163 offset:39936
	global_load_lds_dwordx4 v[246:247], off
	v_lshl_add_u64 v[246:247], s[62:63], 0, v[146:147]
	s_mov_b32 m0, s67
	s_nop 0
	global_load_lds_dwordx4 v[246:247], off
	s_waitcnt vmcnt(8)
	s_waitcnt lgkmcnt(0)
	s_barrier
	s_setprio 2
	v_mfma_f32_16x16x32_bf16 v[126:129], v[156:159], v[208:211], v[126:129]
	v_mfma_f32_16x16x32_bf16 v[122:125], v[168:171], v[208:211], v[122:125]
	v_mfma_f32_16x16x32_bf16 v[110:113], v[156:159], v[216:219], v[110:113]
	v_mfma_f32_16x16x32_bf16 v[106:109], v[168:171], v[216:219], v[106:109]
	v_mfma_f32_16x16x32_bf16 v[94:97], v[156:159], v[224:227], v[94:97]
	v_mfma_f32_16x16x32_bf16 v[90:93], v[168:171], v[224:227], v[90:93]
	v_mfma_f32_16x16x32_bf16 v[78:81], v[156:159], v[232:235], v[78:81]
	v_mfma_f32_16x16x32_bf16 v[74:77], v[168:171], v[232:235], v[74:77]
	s_setprio 0
	s_setprio 2
	v_mfma_f32_16x16x32_bf16 v[126:129], v[164:167], v[212:215], v[126:129]
	v_mfma_f32_16x16x32_bf16 v[122:125], v[172:175], v[212:215], v[122:125]
	v_mfma_f32_16x16x32_bf16 v[110:113], v[164:167], v[220:223], v[110:113]
	v_mfma_f32_16x16x32_bf16 v[106:109], v[172:175], v[220:223], v[106:109]
	v_mfma_f32_16x16x32_bf16 v[94:97], v[164:167], v[228:231], v[94:97]
	v_mfma_f32_16x16x32_bf16 v[90:93], v[172:175], v[228:231], v[90:93]
	v_mfma_f32_16x16x32_bf16 v[78:81], v[164:167], v[236:239], v[78:81]
	v_mfma_f32_16x16x32_bf16 v[74:77], v[172:175], v[236:239], v[74:77]
	s_setprio 0
	s_setprio 2
	v_mfma_f32_16x16x32_bf16 v[118:121], v[176:179], v[208:211], v[118:121]
	v_mfma_f32_16x16x32_bf16 v[114:117], v[184:187], v[208:211], v[114:117]
	v_mfma_f32_16x16x32_bf16 v[102:105], v[176:179], v[216:219], v[102:105]
	v_mfma_f32_16x16x32_bf16 v[98:101], v[184:187], v[216:219], v[98:101]
	v_mfma_f32_16x16x32_bf16 v[86:89], v[176:179], v[224:227], v[86:89]
	v_mfma_f32_16x16x32_bf16 v[82:85], v[184:187], v[224:227], v[82:85]
	v_mfma_f32_16x16x32_bf16 v[70:73], v[176:179], v[232:235], v[70:73]
	v_mfma_f32_16x16x32_bf16 v[66:69], v[184:187], v[232:235], v[66:69]
	s_setprio 0
	s_setprio 2
	v_mfma_f32_16x16x32_bf16 v[118:121], v[180:183], v[212:215], v[118:121]
	v_mfma_f32_16x16x32_bf16 v[114:117], v[204:207], v[212:215], v[114:117]
	v_mfma_f32_16x16x32_bf16 v[102:105], v[180:183], v[220:223], v[102:105]
	v_mfma_f32_16x16x32_bf16 v[98:101], v[204:207], v[220:223], v[98:101]
	v_mfma_f32_16x16x32_bf16 v[86:89], v[180:183], v[228:231], v[86:89]
	v_mfma_f32_16x16x32_bf16 v[82:85], v[204:207], v[228:231], v[82:85]
	v_mfma_f32_16x16x32_bf16 v[70:73], v[180:183], v[236:239], v[70:73]
	v_mfma_f32_16x16x32_bf16 v[66:69], v[204:207], v[236:239], v[66:69]
	s_setprio 1
	s_barrier
; #define PG8_STAGE(bufoff, gbase, voff) do { _Pragma("unroll") for (int _i = 0; _i < 2; ++_i) \
;         __builtin_amdgcn_global_load_lds((const unsigned*)((const char*)(gbase) + (voff)[_i]), (PG8_LAS unsigned*)(lds + (bufoff) + ldsw + _i * 8192), 16, 0, 0); } while (0)
; #define PG8_LDA(dst, b, h) do { _Pragma("unroll") for (int m = 0; m < 4; ++m) _Pragma("unroll") for (int k = 0; k < 2; ++k) dst[m][k] = *(const PG8_LAS bf16x8*)(lds + PG8_SA(b, h) + aoff + m * 2048 + k * 1024); } while (0)
; #define PG8_WAIT_V(n) asm volatile("s_waitcnt vmcnt(" #n ")" ::: "memory")
; template <class Epi, class Sched, bool ALIGN_EPI = false, bool SP2 = false>
; __device__ __forceinline__ void gemm_phase(PG8_LAS unsigned char* lds, const Gemm g, const Sched& S, const Epi& E) {
;     ...
;             PG8_LDA(At, 1, 1); PG8_STAGE(PG8_SB(1, 0), b3, voffB); PG8_STAGE(PG8_SB(1, 1), b3 + hstep, voffB); PG8_STAGE(PG8_SA(1, 0), a3, voffA);
;             PG8_WAIT_V(8); PG8_WAIT_L(0); PG8_BAR; PG8_MMA(1, 0, At, B0); PG8_MMA(1, 1, At, B1); PG8_BAR; PG8_SCHED;
;             } else {
;             PG8_LDB(B0, 0, 0); PG8_SCHED; PG8_LDA(At, 0, 0); PG8_STAGE(PG8_SA(1, 1), a1 + hstep, voffA);
;             PG8_WAIT_L(8); PG8_BAR; PG8_WAIT_L(0); PG8_MMA(0, 0, At, B0); PG8_BAR; PG8_SCHED;
;             PG8_LDB(B1, 0, 1); PG8_STAGE(PG8_SB(0, 0), b2, voffB);
;             PG8_BAR; PG8_WAIT_L(0); PG8_MMA(0, 1, At, B1); PG8_BAR;
;             PG8_LDA(At, 0, 1); PG8_STAGE(PG8_SA(0, 0), a2, voffA);
;             PG8_BAR; PG8_WAIT_L(0); PG8_MMA(1, 0, At, B0); PG8_BAR; PG8_SCHED;
;             PG8_STAGE(PG8_SB(0, 1), b2 + hstep, voffB);
;             PG8_WAIT_V(6); PG8_BAR; PG8_MMA(1, 1, At, B1); PG8_BAR;
;             PG8_LDB(B0, 1, 0); PG8_SCHED; PG8_LDA(At, 1, 0); PG8_STAGE(PG8_SA(0, 1), a2 + hstep, voffA);
;             PG8_WAIT_L(8); PG8_BAR; PG8_WAIT_L(0); PG8_MMA(0, 0, At, B0); PG8_BAR; PG8_SCHED;
;             PG8_LDB(B1, 1, 1); PG8_STAGE(PG8_SB(1, 0), b3, voffB);
;             PG8_BAR; PG8_WAIT_L(0); PG8_MMA(0, 1, At, B1); PG8_BAR;
;             PG8_LDA(At, 1, 1); PG8_STAGE(PG8_SA(1, 0), a3, voffA);
;             PG8_BAR; PG8_WAIT_L(0); PG8_MMA(1, 0, At, B0); PG8_BAR; PG8_SCHED;
;             PG8_STAGE(PG8_SB(1, 1), b3 + hstep, voffB);
;             PG8_WAIT_V(6); PG8_BAR; PG8_MMA(1, 1, At, B1); PG8_BAR;
;             }
;         }
;         if constexpr (ALIGN_EPI) { if (wr == 0) PG8_BAR; }
	s_add_i32 s47, s47, s4
	v_lshl_add_u64 v[160:161], v[160:161], 0, s[68:69]
	s_mov_b32 m0, s47
	ds_read_b128 v[208:211], v163 offset:49152
	ds_read_b128 v[212:215], v163 offset:50176
	ds_read_b128 v[216:219], v163 offset:51200
	ds_read_b128 v[220:223], v163 offset:52224
	ds_read_b128 v[224:227], v163 offset:53248
	ds_read_b128 v[228:231], v163 offset:54272
	ds_read_b128 v[232:235], v163 offset:55296
	ds_read_b128 v[236:239], v163 offset:56320
	global_load_lds_dwordx4 v[160:161], off
	s_add_i32 m0, s47, 0x2000
	s_add_u32 s18, s18, 0x200080
	v_lshl_add_u64 v[160:161], v[240:241], 0, s[68:69]
	s_addc_u32 s19, s19, 0
	s_add_i32 s47, s76, s4
	global_load_lds_dwordx4 v[160:161], off
	v_lshl_add_u64 v[160:161], s[18:19], 0, v[148:149]
	s_mov_b32 m0, s47
	s_nop 0
	global_load_lds_dwordx4 v[160:161], off
	v_lshl_add_u64 v[160:161], s[18:19], 0, v[144:145]
	s_add_i32 m0, s47, 0x2000
	s_nop 0
	global_load_lds_dwordx4 v[160:161], off
	v_lshl_add_u64 v[160:161], v[242:243], 0, s[68:69]
	s_mov_b32 m0, s1
	s_nop 0
	global_load_lds_dwordx4 v[160:161], off
	v_lshl_add_u64 v[160:161], v[244:245], 0, s[68:69]
	s_mov_b32 m0, s60
	s_nop 0
	global_load_lds_dwordx4 v[160:161], off
	s_nop 0
	s_waitcnt vmcnt(8)
	s_waitcnt lgkmcnt(0)
	s_barrier
	s_setprio 2
	v_mfma_f32_16x16x32_bf16 v[62:65], v[156:159], v[208:211], v[62:65]
	v_mfma_f32_16x16x32_bf16 v[58:61], v[168:171], v[208:211], v[58:61]
	v_mfma_f32_16x16x32_bf16 v[46:49], v[156:159], v[216:219], v[46:49]
	v_mfma_f32_16x16x32_bf16 v[42:45], v[168:171], v[216:219], v[42:45]
	v_mfma_f32_16x16x32_bf16 v[30:33], v[156:159], v[224:227], v[30:33]
	v_mfma_f32_16x16x32_bf16 v[26:29], v[168:171], v[224:227], v[26:29]
	v_mfma_f32_16x16x32_bf16 v[14:17], v[156:159], v[232:235], v[14:17]
	v_mfma_f32_16x16x32_bf16 v[10:13], v[168:171], v[232:235], v[10:13]
	s_setprio 0
	s_setprio 2
	v_mfma_f32_16x16x32_bf16 v[62:65], v[164:167], v[212:215], v[62:65]
	v_mfma_f32_16x16x32_bf16 v[58:61], v[172:175], v[212:215], v[58:61]
	v_mfma_f32_16x16x32_bf16 v[46:49], v[164:167], v[220:223], v[46:49]
	v_mfma_f32_16x16x32_bf16 v[42:45], v[172:175], v[220:223], v[42:45]
	v_mfma_f32_16x16x32_bf16 v[30:33], v[164:167], v[228:231], v[30:33]
	v_mfma_f32_16x16x32_bf16 v[26:29], v[172:175], v[228:231], v[26:29]
	v_mfma_f32_16x16x32_bf16 v[14:17], v[164:167], v[236:239], v[14:17]
	v_mfma_f32_16x16x32_bf16 v[10:13], v[172:175], v[236:239], v[10:13]
	s_setprio 0
	s_setprio 2
	v_mfma_f32_16x16x32_bf16 v[54:57], v[176:179], v[208:211], v[54:57]
	v_mfma_f32_16x16x32_bf16 v[50:53], v[184:187], v[208:211], v[50:53]
	v_mfma_f32_16x16x32_bf16 v[38:41], v[176:179], v[216:219], v[38:41]
	v_mfma_f32_16x16x32_bf16 v[34:37], v[184:187], v[216:219], v[34:37]
	v_mfma_f32_16x16x32_bf16 v[22:25], v[176:179], v[224:227], v[22:25]
	v_mfma_f32_16x16x32_bf16 v[18:21], v[184:187], v[224:227], v[18:21]
	v_mfma_f32_16x16x32_bf16 v[6:9], v[176:179], v[232:235], v[6:9]
	v_mfma_f32_16x16x32_bf16 v[2:5], v[184:187], v[232:235], v[2:5]
	s_setprio 0
	s_setprio 2
	v_mfma_f32_16x16x32_bf16 v[54:57], v[180:183], v[212:215], v[54:57]
	v_mfma_f32_16x16x32_bf16 v[50:53], v[204:207], v[212:215], v[50:53]
	v_mfma_f32_16x16x32_bf16 v[38:41], v[180:183], v[220:223], v[38:41]
	v_mfma_f32_16x16x32_bf16 v[34:37], v[204:207], v[220:223], v[34:37]
	v_mfma_f32_16x16x32_bf16 v[22:25], v[180:183], v[228:231], v[22:25]
	v_mfma_f32_16x16x32_bf16 v[18:21], v[204:207], v[228:231], v[18:21]
	v_mfma_f32_16x16x32_bf16 v[6:9], v[180:183], v[236:239], v[6:9]
	v_mfma_f32_16x16x32_bf16 v[2:5], v[204:207], v[236:239], v[2:5]
	s_setprio 1
	s_barrier
	s_add_i32 s46, s46, 2
	s_add_u32 s58, s58, 0x100
	s_addc_u32 s59, s59, 0
	s_add_u32 s78, s78, 0x100
	s_addc_u32 s79, s79, 0
	s_cmpk_gt_u32 s46, 0x7d
	s_cbranch_scc0 .LBB0_36
	s_and_b64 vcc, exec, s[12:13]
	s_cbranch_vccz .LBB0_39
	s_barrier

; #define PG8_STAGE(bufoff, gbase, voff) do { _Pragma("unroll") for (int _i = 0; _i < 2; ++_i) \
;         __builtin_amdgcn_global_load_lds((const unsigned*)((const char*)(gbase) + (voff)[_i]), (PG8_LAS unsigned*)(lds + (bufoff) + ldsw + _i * 8192), 16, 0, 0); } while (0)
; #define PG8_LDA(dst, b, h) do { _Pragma("unroll") for (int m = 0; m < 4; ++m) _Pragma("unroll") for (int k = 0; k < 2; ++k) dst[m][k] = *(const PG8_LAS bf16x8*)(lds + PG8_SA(b, h) + aoff + m * 2048 + k * 1024); } while (0)
; #define PG8_LDB(dst, b, h) do { _Pragma("unroll") for (int n = 0; n < 2; ++n) _Pragma("unroll") for (int k = 0; k < 2; ++k) dst[n][k] = *(const PG8_LAS bf16x8*)(lds + PG8_SB(b, h) + boff + n * 2048 + k * 1024); } while (0)
; #define PG8_MMA(ai, bj, At, Bt) do { __builtin_amdgcn_s_setprio(1); _Pragma("unroll") for (int m = 0; m < 4; ++m) _Pragma("unroll") for (int n = 0; n < 2; ++n) _Pragma("unroll") for (int k = 0; k < 2; ++k) \
;         acc[ai][bj][m][n] = __builtin_amdgcn_mfma_f32_16x16x32_bf16(Bt[n][k], At[m][k], acc[ai][bj][m][n], 0, 0, 0); __builtin_amdgcn_s_setprio(0); } while (0)
; #define PG8_WAIT_V(n) asm volatile("s_waitcnt vmcnt(" #n ")" ::: "memory")
; #define PG8_BAR __builtin_amdgcn_s_barrier()
; template <class Epi, class Sched, bool ALIGN_EPI = false, bool SP2 = false>
; __device__ __forceinline__ void gemm_phase(PG8_LAS unsigned char* lds, const Gemm g, const Sched& S, const Epi& E) {
;     ...
;         for (int t = 0; t < nt; t += 2) {
;             const bool last = (t == nt - 2);
;             const char* a1 = cA + (size_t)(t + 1) * kstep;
;             const char* a2 = last ? nA : cA + (size_t)(t + 2) * kstep; const char* b2 = last ? nB : cB + (size_t)(t + 2) * kstep;
;             const char* a3 = a2 + kstep; const char* b3 = b2 + kstep;
;             if (last && has_next) S.a_ready(nxt);
;             if constexpr (SP2) {
;             PG8_LDB(B0, 0, 0); PG8_LDB(B1, 0, 1); PG8_SCHED; PG8_LDA(At, 0, 0); PG8_STAGE(PG8_SA(1, 1), a1 + hstep, voffA);
;             PG8_WAIT_V(8); PG8_WAIT_L(0); PG8_BAR; PG8_MMA(0, 0, At, B0); PG8_MMA(0, 1, At, B1); PG8_BAR; PG8_SCHED;
;             PG8_LDA(At, 0, 1); PG8_STAGE(PG8_SB(0, 0), b2, voffB); PG8_STAGE(PG8_SB(0, 1), b2 + hstep, voffB); PG8_STAGE(PG8_SA(0, 0), a2, voffA);
;             PG8_WAIT_V(8); PG8_WAIT_L(0); PG8_BAR; PG8_MMA(1, 0, At, B0); PG8_MMA(1, 1, At, B1); PG8_BAR; PG8_SCHED;
.LBB0_76:
	s_add_u32 s18, s0, 0xfff80080
	s_addc_u32 s19, s1, -1
	s_add_i32 s47, 0, 0x10000
	s_cmp_eq_u32 s46, 28
	s_cselect_b32 s59, s60, s19
	s_cselect_b32 s58, s73, s18
	v_add_u32_e32 v158, s47, v143
	s_cselect_b32 s19, s45, s79
	s_cselect_b32 s18, s84, s78
	s_add_i32 s80, 0, 0x14000
	ds_read_b128 v[162:165], v158
	ds_read_b128 v[166:169], v158 offset:1024
	ds_read_b128 v[170:173], v158 offset:2048
	ds_read_b128 v[174:177], v158 offset:3072
	v_add_u32_e32 v158, s80, v143
	ds_read_b128 v[178:181], v158
	ds_read_b128 v[182:185], v158 offset:1024
	ds_read_b128 v[204:207], v158 offset:2048
	ds_read_b128 v[208:211], v158 offset:3072
	v_lshl_add_u64 v[158:159], s[0:1], 0, v[154:155]
	s_add_i32 m0, s62, 0xc000
	ds_read_b128 v[212:215], v161
	ds_read_b128 v[216:219], v161 offset:1024
	ds_read_b128 v[220:223], v161 offset:2048
	ds_read_b128 v[224:227], v161 offset:3072
	ds_read_b128 v[228:231], v161 offset:4096
	ds_read_b128 v[232:235], v161 offset:5120
	ds_read_b128 v[236:239], v161 offset:6144
	ds_read_b128 v[240:243], v161 offset:7168
	global_load_lds_dwordx4 v[158:159], off
	v_lshl_add_u64 v[158:159], s[0:1], 0, v[156:157]
	s_add_i32 m0, s62, 0xe000
	s_nop 0
	global_load_lds_dwordx4 v[158:159], off
	s_nop 0
	s_waitcnt vmcnt(8)
	s_waitcnt lgkmcnt(0)
	s_barrier
	s_setprio 2
	v_mfma_f32_16x16x32_bf16 v[126:129], v[162:165], v[212:215], v[126:129]
	v_mfma_f32_16x16x32_bf16 v[122:125], v[170:173], v[212:215], v[122:125]
	v_mfma_f32_16x16x32_bf16 v[110:113], v[162:165], v[220:223], v[110:113]
	v_mfma_f32_16x16x32_bf16 v[106:109], v[170:173], v[220:223], v[106:109]
	v_mfma_f32_16x16x32_bf16 v[94:97], v[162:165], v[228:231], v[94:97]
	v_mfma_f32_16x16x32_bf16 v[90:93], v[170:173], v[228:231], v[90:93]
	v_mfma_f32_16x16x32_bf16 v[78:81], v[162:165], v[236:239], v[78:81]
	v_mfma_f32_16x16x32_bf16 v[74:77], v[170:173], v[236:239], v[74:77]
	s_setprio 0
	s_setprio 2
	v_mfma_f32_16x16x32_bf16 v[126:129], v[166:169], v[216:219], v[126:129]
	v_mfma_f32_16x16x32_bf16 v[122:125], v[174:177], v[216:219], v[122:125]
	v_mfma_f32_16x16x32_bf16 v[110:113], v[166:169], v[224:227], v[110:113]
	v_mfma_f32_16x16x32_bf16 v[106:109], v[174:177], v[224:227], v[106:109]
	v_mfma_f32_16x16x32_bf16 v[94:97], v[166:169], v[232:235], v[94:97]
	v_mfma_f32_16x16x32_bf16 v[90:93], v[174:177], v[232:235], v[90:93]
	v_mfma_f32_16x16x32_bf16 v[78:81], v[166:169], v[240:243], v[78:81]
	v_mfma_f32_16x16x32_bf16 v[74:77], v[174:177], v[240:243], v[74:77]
	s_setprio 0
	s_setprio 2
	v_mfma_f32_16x16x32_bf16 v[118:121], v[178:181], v[212:215], v[118:121]
	v_mfma_f32_16x16x32_bf16 v[114:117], v[204:207], v[212:215], v[114:117]
	v_mfma_f32_16x16x32_bf16 v[102:105], v[178:181], v[220:223], v[102:105]
	v_mfma_f32_16x16x32_bf16 v[98:101], v[204:207], v[220:223], v[98:101]
	v_mfma_f32_16x16x32_bf16 v[86:89], v[178:181], v[228:231], v[86:89]
	v_mfma_f32_16x16x32_bf16 v[82:85], v[204:207], v[228:231], v[82:85]
	v_mfma_f32_16x16x32_bf16 v[70:73], v[178:181], v[236:239], v[70:73]
	v_mfma_f32_16x16x32_bf16 v[66:69], v[204:207], v[236:239], v[66:69]
	s_setprio 0
	s_setprio 2
	v_mfma_f32_16x16x32_bf16 v[118:121], v[182:185], v[216:219], v[118:121]
	v_mfma_f32_16x16x32_bf16 v[114:117], v[208:211], v[216:219], v[114:117]
	v_mfma_f32_16x16x32_bf16 v[102:105], v[182:185], v[224:227], v[102:105]
	v_mfma_f32_16x16x32_bf16 v[98:101], v[208:211], v[224:227], v[98:101]
	v_mfma_f32_16x16x32_bf16 v[86:89], v[182:185], v[232:235], v[86:89]
	v_mfma_f32_16x16x32_bf16 v[82:85], v[208:211], v[232:235], v[82:85]
	v_mfma_f32_16x16x32_bf16 v[70:73], v[182:185], v[240:243], v[70:73]
	v_mfma_f32_16x16x32_bf16 v[66:69], v[208:211], v[240:243], v[66:69]
	s_setprio 1
	s_barrier
	s_add_i32 s47, s47, s54
	v_lshl_add_u64 v[158:159], s[18:19], 0, v[148:149]
	s_mov_b32 m0, s47
	ds_read_b128 v[212:215], v161 offset:16384
	ds_read_b128 v[216:219], v161 offset:17408
	ds_read_b128 v[220:223], v161 offset:18432
	ds_read_b128 v[224:227], v161 offset:19456
	ds_read_b128 v[228:231], v161 offset:20480
	ds_read_b128 v[232:235], v161 offset:21504
	ds_read_b128 v[236:239], v161 offset:22528
	ds_read_b128 v[240:243], v161 offset:23552
	global_load_lds_dwordx4 v[158:159], off
	s_add_i32 m0, s47, 0x2000
	s_add_u32 s76, s18, 0x80000
	v_lshl_add_u64 v[186:187], s[18:19], 0, v[144:145]
	s_addc_u32 s77, s19, 0
	s_add_i32 s47, s80, s54
	global_load_lds_dwordx4 v[186:187], off
	v_lshl_add_u64 v[244:245], s[76:77], 0, v[148:149]
	s_mov_b32 m0, s47
	v_lshl_add_u64 v[246:247], s[58:59], 0, v[146:147]
	global_load_lds_dwordx4 v[244:245], off
	v_lshl_add_u64 v[244:245], s[76:77], 0, v[144:145]
	s_add_i32 m0, s47, 0x2000
	s_nop 0
	global_load_lds_dwordx4 v[244:245], off
	v_lshl_add_u64 v[244:245], s[58:59], 0, v[150:151]
	s_mov_b32 m0, s62
	s_nop 0
	global_load_lds_dwordx4 v[244:245], off
	s_mov_b32 m0, s63
	s_nop 0
	global_load_lds_dwordx4 v[246:247], off
	s_waitcnt vmcnt(8)
	s_waitcnt lgkmcnt(0)
	s_barrier
; #define PG8_STAGE(bufoff, gbase, voff) do { _Pragma("unroll") for (int _i = 0; _i < 2; ++_i) \
;         __builtin_amdgcn_global_load_lds((const unsigned*)((const char*)(gbase) + (voff)[_i]), (PG8_LAS unsigned*)(lds + (bufoff) + ldsw + _i * 8192), 16, 0, 0); } while (0)
; #define PG8_LDA(dst, b, h) do { _Pragma("unroll") for (int m = 0; m < 4; ++m) _Pragma("unroll") for (int k = 0; k < 2; ++k) dst[m][k] = *(const PG8_LAS bf16x8*)(lds + PG8_SA(b, h) + aoff + m * 2048 + k * 1024); } while (0)
; #define PG8_LDB(dst, b, h) do { _Pragma("unroll") for (int n = 0; n < 2; ++n) _Pragma("unroll") for (int k = 0; k < 2; ++k) dst[n][k] = *(const PG8_LAS bf16x8*)(lds + PG8_SB(b, h) + boff + n * 2048 + k * 1024); } while (0)
; #define PG8_MMA(ai, bj, At, Bt) do { __builtin_amdgcn_s_setprio(1); _Pragma("unroll") for (int m = 0; m < 4; ++m) _Pragma("unroll") for (int n = 0; n < 2; ++n) _Pragma("unroll") for (int k = 0; k < 2; ++k) \
;         acc[ai][bj][m][n] = __builtin_amdgcn_mfma_f32_16x16x32_bf16(Bt[n][k], At[m][k], acc[ai][bj][m][n], 0, 0, 0); __builtin_amdgcn_s_setprio(0); } while (0)
; #define PG8_WAIT_V(n) asm volatile("s_waitcnt vmcnt(" #n ")" ::: "memory")
; #define PG8_WAIT_L(n) asm volatile("s_waitcnt lgkmcnt(" #n ")" ::: "memory")
; #define PG8_BAR __builtin_amdgcn_s_barrier()
; #define PG8_SCHED __builtin_amdgcn_sched_barrier(0)
; template <class Epi, class Sched, bool ALIGN_EPI = false, bool SP2 = false>
; __device__ __forceinline__ void gemm_phase(PG8_LAS unsigned char* lds, const Gemm g, const Sched& S, const Epi& E) {
;     ...
;             PG8_WAIT_V(8); PG8_WAIT_L(0); PG8_BAR; PG8_MMA(1, 0, At, B0); PG8_MMA(1, 1, At, B1); PG8_BAR; PG8_SCHED;
;             PG8_LDB(B0, 1, 0); PG8_LDB(B1, 1, 1); PG8_SCHED; PG8_LDA(At, 1, 0); PG8_STAGE(PG8_SA(0, 1), a2 + hstep, voffA);
;             PG8_WAIT_V(8); PG8_WAIT_L(0); PG8_BAR; PG8_MMA(0, 0, At, B0); PG8_MMA(0, 1, At, B1); PG8_BAR; PG8_SCHED;
	s_setprio 2
	v_mfma_f32_16x16x32_bf16 v[62:65], v[162:165], v[212:215], v[62:65]
	v_mfma_f32_16x16x32_bf16 v[58:61], v[170:173], v[212:215], v[58:61]
	v_mfma_f32_16x16x32_bf16 v[46:49], v[162:165], v[220:223], v[46:49]
	v_mfma_f32_16x16x32_bf16 v[42:45], v[170:173], v[220:223], v[42:45]
	v_mfma_f32_16x16x32_bf16 v[30:33], v[162:165], v[228:231], v[30:33]
	v_mfma_f32_16x16x32_bf16 v[26:29], v[170:173], v[228:231], v[26:29]
	v_mfma_f32_16x16x32_bf16 v[14:17], v[162:165], v[236:239], v[14:17]
	v_mfma_f32_16x16x32_bf16 v[10:13], v[170:173], v[236:239], v[10:13]
	s_setprio 0
	s_setprio 2
	v_mfma_f32_16x16x32_bf16 v[62:65], v[166:169], v[216:219], v[62:65]
	v_mfma_f32_16x16x32_bf16 v[58:61], v[174:177], v[216:219], v[58:61]
	v_mfma_f32_16x16x32_bf16 v[46:49], v[166:169], v[224:227], v[46:49]
	v_mfma_f32_16x16x32_bf16 v[42:45], v[174:177], v[224:227], v[42:45]
	v_mfma_f32_16x16x32_bf16 v[30:33], v[166:169], v[232:235], v[30:33]
	v_mfma_f32_16x16x32_bf16 v[26:29], v[174:177], v[232:235], v[26:29]
	v_mfma_f32_16x16x32_bf16 v[14:17], v[166:169], v[240:243], v[14:17]
	v_mfma_f32_16x16x32_bf16 v[10:13], v[174:177], v[240:243], v[10:13]
	s_setprio 0
	s_setprio 2
	v_mfma_f32_16x16x32_bf16 v[54:57], v[178:181], v[212:215], v[54:57]
	v_mfma_f32_16x16x32_bf16 v[50:53], v[204:207], v[212:215], v[50:53]
	v_mfma_f32_16x16x32_bf16 v[38:41], v[178:181], v[220:223], v[38:41]
	v_mfma_f32_16x16x32_bf16 v[34:37], v[204:207], v[220:223], v[34:37]
	v_mfma_f32_16x16x32_bf16 v[22:25], v[178:181], v[228:231], v[22:25]
	v_mfma_f32_16x16x32_bf16 v[18:21], v[204:207], v[228:231], v[18:21]
	v_mfma_f32_16x16x32_bf16 v[6:9], v[178:181], v[236:239], v[6:9]
	v_mfma_f32_16x16x32_bf16 v[2:5], v[204:207], v[236:239], v[2:5]
	s_setprio 0
	s_setprio 2
	v_mfma_f32_16x16x32_bf16 v[54:57], v[182:185], v[216:219], v[54:57]
	v_mfma_f32_16x16x32_bf16 v[50:53], v[208:211], v[216:219], v[50:53]
	v_mfma_f32_16x16x32_bf16 v[38:41], v[182:185], v[224:227], v[38:41]
	v_mfma_f32_16x16x32_bf16 v[34:37], v[208:211], v[224:227], v[34:37]
	v_mfma_f32_16x16x32_bf16 v[22:25], v[182:185], v[232:235], v[22:25]
	v_mfma_f32_16x16x32_bf16 v[18:21], v[208:211], v[232:235], v[18:21]
	v_mfma_f32_16x16x32_bf16 v[6:9], v[182:185], v[240:243], v[6:9]
	v_mfma_f32_16x16x32_bf16 v[2:5], v[208:211], v[240:243], v[2:5]
	s_setprio 1
	s_barrier
	s_add_i32 s47, 0, 0x18000
	s_add_i32 s76, 0, 0x1c000
	v_add_u32_e32 v174, s47, v143
	v_add_u32_e32 v203, s76, v143
	ds_read_b128 v[162:165], v174
	ds_read_b128 v[166:169], v174 offset:1024
	ds_read_b128 v[170:173], v174 offset:2048
	ds_read_b128 v[174:177], v174 offset:3072
	ds_read_b128 v[178:181], v203
	ds_read_b128 v[182:185], v203 offset:1024
	ds_read_b128 v[204:207], v203 offset:2048
	ds_read_b128 v[208:211], v203 offset:3072
	s_add_u32 s58, s58, 0x80000
	s_addc_u32 s59, s59, 0
	s_mov_b32 m0, s67
	v_lshl_add_u64 v[248:249], s[58:59], 0, v[150:151]
	ds_read_b128 v[212:215], v161 offset:32768
	ds_read_b128 v[216:219], v161 offset:33792
	ds_read_b128 v[220:223], v161 offset:34816
	ds_read_b128 v[224:227], v161 offset:35840
	ds_read_b128 v[228:231], v161 offset:36864
	ds_read_b128 v[232:235], v161 offset:37888
	ds_read_b128 v[236:239], v161 offset:38912
	ds_read_b128 v[240:243], v161 offset:39936
	global_load_lds_dwordx4 v[248:249], off
	v_lshl_add_u64 v[248:249], s[58:59], 0, v[146:147]
	s_mov_b32 m0, s4
	s_nop 0
	global_load_lds_dwordx4 v[248:249], off
	s_waitcnt vmcnt(8)
	s_waitcnt lgkmcnt(0)
	s_barrier
	s_setprio 2
	v_mfma_f32_16x16x32_bf16 v[126:129], v[162:165], v[212:215], v[126:129]
	v_mfma_f32_16x16x32_bf16 v[122:125], v[170:173], v[212:215], v[122:125]
	v_mfma_f32_16x16x32_bf16 v[110:113], v[162:165], v[220:223], v[110:113]
	v_mfma_f32_16x16x32_bf16 v[106:109], v[170:173], v[220:223], v[106:109]
	v_mfma_f32_16x16x32_bf16 v[94:97], v[162:165], v[228:231], v[94:97]
	v_mfma_f32_16x16x32_bf16 v[90:93], v[170:173], v[228:231], v[90:93]
	v_mfma_f32_16x16x32_bf16 v[78:81], v[162:165], v[236:239], v[78:81]
	v_mfma_f32_16x16x32_bf16 v[74:77], v[170:173], v[236:239], v[74:77]
	s_setprio 0
	s_setprio 2
	v_mfma_f32_16x16x32_bf16 v[126:129], v[166:169], v[216:219], v[126:129]
	v_mfma_f32_16x16x32_bf16 v[122:125], v[174:177], v[216:219], v[122:125]
	v_mfma_f32_16x16x32_bf16 v[110:113], v[166:169], v[224:227], v[110:113]
	v_mfma_f32_16x16x32_bf16 v[106:109], v[174:177], v[224:227], v[106:109]
	v_mfma_f32_16x16x32_bf16 v[94:97], v[166:169], v[232:235], v[94:97]
	v_mfma_f32_16x16x32_bf16 v[90:93], v[174:177], v[232:235], v[90:93]
	v_mfma_f32_16x16x32_bf16 v[78:81], v[166:169], v[240:243], v[78:81]
	v_mfma_f32_16x16x32_bf16 v[74:77], v[174:177], v[240:243], v[74:77]
	s_setprio 0
	s_setprio 2
	v_mfma_f32_16x16x32_bf16 v[118:121], v[178:181], v[212:215], v[118:121]
	v_mfma_f32_16x16x32_bf16 v[114:117], v[204:207], v[212:215], v[114:117]
	v_mfma_f32_16x16x32_bf16 v[102:105], v[178:181], v[220:223], v[102:105]
	v_mfma_f32_16x16x32_bf16 v[98:101], v[204:207], v[220:223], v[98:101]
	v_mfma_f32_16x16x32_bf16 v[86:89], v[178:181], v[228:231], v[86:89]
	v_mfma_f32_16x16x32_bf16 v[82:85], v[204:207], v[228:231], v[82:85]
	v_mfma_f32_16x16x32_bf16 v[70:73], v[178:181], v[236:239], v[70:73]
	v_mfma_f32_16x16x32_bf16 v[66:69], v[204:207], v[236:239], v[66:69]
	s_setprio 0
	s_setprio 2
	v_mfma_f32_16x16x32_bf16 v[118:121], v[182:185], v[216:219], v[118:121]
	v_mfma_f32_16x16x32_bf16 v[114:117], v[208:211], v[216:219], v[114:117]
	v_mfma_f32_16x16x32_bf16 v[102:105], v[182:185], v[224:227], v[102:105]
	v_mfma_f32_16x16x32_bf16 v[98:101], v[208:211], v[224:227], v[98:101]
	v_mfma_f32_16x16x32_bf16 v[86:89], v[182:185], v[232:235], v[86:89]
	v_mfma_f32_16x16x32_bf16 v[82:85], v[208:211], v[232:235], v[82:85]
	v_mfma_f32_16x16x32_bf16 v[70:73], v[182:185], v[240:243], v[70:73]
	v_mfma_f32_16x16x32_bf16 v[66:69], v[208:211], v[240:243], v[66:69]
	s_setprio 1
	s_barrier
; #define PG8_STAGE(bufoff, gbase, voff) do { _Pragma("unroll") for (int _i = 0; _i < 2; ++_i) \
;         __builtin_amdgcn_global_load_lds((const unsigned*)((const char*)(gbase) + (voff)[_i]), (PG8_LAS unsigned*)(lds + (bufoff) + ldsw + _i * 8192), 16, 0, 0); } while (0)
; #define PG8_LDA(dst, b, h) do { _Pragma("unroll") for (int m = 0; m < 4; ++m) _Pragma("unroll") for (int k = 0; k < 2; ++k) dst[m][k] = *(const PG8_LAS bf16x8*)(lds + PG8_SA(b, h) + aoff + m * 2048 + k * 1024); } while (0)
; #define PG8_WAIT_V(n) asm volatile("s_waitcnt vmcnt(" #n ")" ::: "memory")
; template <class Epi, class Sched, bool ALIGN_EPI = false, bool SP2 = false>
; __device__ __forceinline__ void gemm_phase(PG8_LAS unsigned char* lds, const Gemm g, const Sched& S, const Epi& E) {
;     ...
;             PG8_LDA(At, 1, 1); PG8_STAGE(PG8_SB(1, 0), b3, voffB); PG8_STAGE(PG8_SB(1, 1), b3 + hstep, voffB); PG8_STAGE(PG8_SA(1, 0), a3, voffA);
;             PG8_WAIT_V(8); PG8_WAIT_L(0); PG8_BAR; PG8_MMA(1, 0, At, B0); PG8_MMA(1, 1, At, B1); PG8_BAR; PG8_SCHED;
;             } else {
;             PG8_LDB(B0, 0, 0); PG8_SCHED; PG8_LDA(At, 0, 0); PG8_STAGE(PG8_SA(1, 1), a1 + hstep, voffA);
;             PG8_WAIT_L(8); PG8_BAR; PG8_WAIT_L(0); PG8_MMA(0, 0, At, B0); PG8_BAR; PG8_SCHED;
;             PG8_LDB(B1, 0, 1); PG8_STAGE(PG8_SB(0, 0), b2, voffB);
;             PG8_BAR; PG8_WAIT_L(0); PG8_MMA(0, 1, At, B1); PG8_BAR;
;             PG8_LDA(At, 0, 1); PG8_STAGE(PG8_SA(0, 0), a2, voffA);
;             PG8_BAR; PG8_WAIT_L(0); PG8_MMA(1, 0, At, B0); PG8_BAR; PG8_SCHED;
;             PG8_STAGE(PG8_SB(0, 1), b2 + hstep, voffB);
;             PG8_WAIT_V(6); PG8_BAR; PG8_MMA(1, 1, At, B1); PG8_BAR;
;             PG8_LDB(B0, 1, 0); PG8_SCHED; PG8_LDA(At, 1, 0); PG8_STAGE(PG8_SA(0, 1), a2 + hstep, voffA);
;             PG8_WAIT_L(8); PG8_BAR; PG8_WAIT_L(0); PG8_MMA(0, 0, At, B0); PG8_BAR; PG8_SCHED;
;             PG8_LDB(B1, 1, 1); PG8_STAGE(PG8_SB(1, 0), b3, voffB);
;             PG8_BAR; PG8_WAIT_L(0); PG8_MMA(0, 1, At, B1); PG8_BAR;
;             PG8_LDA(At, 1, 1); PG8_STAGE(PG8_SA(1, 0), a3, voffA);
;             PG8_BAR; PG8_WAIT_L(0); PG8_MMA(1, 0, At, B0); PG8_BAR; PG8_SCHED;
;             PG8_STAGE(PG8_SB(1, 1), b3 + hstep, voffB);
;             PG8_WAIT_V(6); PG8_BAR; PG8_MMA(1, 1, At, B1); PG8_BAR;
;             }
;         }
;         if constexpr (ALIGN_EPI) { if (wr == 0) PG8_BAR; }
	s_add_i32 s47, s47, s54
	v_lshl_add_u64 v[158:159], v[158:159], 0, s[68:69]
	s_mov_b32 m0, s47
	ds_read_b128 v[212:215], v161 offset:49152
	ds_read_b128 v[216:219], v161 offset:50176
	ds_read_b128 v[220:223], v161 offset:51200
	ds_read_b128 v[224:227], v161 offset:52224
	ds_read_b128 v[228:231], v161 offset:53248
	ds_read_b128 v[232:235], v161 offset:54272
	ds_read_b128 v[236:239], v161 offset:55296
	ds_read_b128 v[240:243], v161 offset:56320
	global_load_lds_dwordx4 v[158:159], off
	s_add_i32 m0, s47, 0x2000
	s_add_u32 s18, s18, 0x80080
	v_lshl_add_u64 v[158:159], v[186:187], 0, s[68:69]
	s_addc_u32 s19, s19, 0
	s_add_i32 s47, s76, s54
	global_load_lds_dwordx4 v[158:159], off
	v_lshl_add_u64 v[158:159], s[18:19], 0, v[148:149]
	s_mov_b32 m0, s47
	s_nop 0
	global_load_lds_dwordx4 v[158:159], off
	v_lshl_add_u64 v[158:159], s[18:19], 0, v[144:145]
	s_add_i32 m0, s47, 0x2000
	s_nop 0
	global_load_lds_dwordx4 v[158:159], off
	v_lshl_add_u64 v[158:159], v[244:245], 0, s[68:69]
	s_mov_b32 m0, s5
	s_nop 0
	global_load_lds_dwordx4 v[158:159], off
	v_lshl_add_u64 v[158:159], v[246:247], 0, s[68:69]
	s_mov_b32 m0, s57
	s_nop 0
	global_load_lds_dwordx4 v[158:159], off
	s_nop 0
	s_waitcnt vmcnt(8)
	s_waitcnt lgkmcnt(0)
	s_barrier
	s_setprio 2
	v_mfma_f32_16x16x32_bf16 v[62:65], v[162:165], v[212:215], v[62:65]
	v_mfma_f32_16x16x32_bf16 v[58:61], v[170:173], v[212:215], v[58:61]
	v_mfma_f32_16x16x32_bf16 v[46:49], v[162:165], v[220:223], v[46:49]
	v_mfma_f32_16x16x32_bf16 v[42:45], v[170:173], v[220:223], v[42:45]
	v_mfma_f32_16x16x32_bf16 v[30:33], v[162:165], v[228:231], v[30:33]
	v_mfma_f32_16x16x32_bf16 v[26:29], v[170:173], v[228:231], v[26:29]
	v_mfma_f32_16x16x32_bf16 v[14:17], v[162:165], v[236:239], v[14:17]
	v_mfma_f32_16x16x32_bf16 v[10:13], v[170:173], v[236:239], v[10:13]
	s_setprio 0
	s_setprio 2
	v_mfma_f32_16x16x32_bf16 v[62:65], v[166:169], v[216:219], v[62:65]
	v_mfma_f32_16x16x32_bf16 v[58:61], v[174:177], v[216:219], v[58:61]
	v_mfma_f32_16x16x32_bf16 v[46:49], v[166:169], v[224:227], v[46:49]
	v_mfma_f32_16x16x32_bf16 v[42:45], v[174:177], v[224:227], v[42:45]
	v_mfma_f32_16x16x32_bf16 v[30:33], v[166:169], v[232:235], v[30:33]
	v_mfma_f32_16x16x32_bf16 v[26:29], v[174:177], v[232:235], v[26:29]
	v_mfma_f32_16x16x32_bf16 v[14:17], v[166:169], v[240:243], v[14:17]
	v_mfma_f32_16x16x32_bf16 v[10:13], v[174:177], v[240:243], v[10:13]
	s_setprio 0
	s_setprio 2
	v_mfma_f32_16x16x32_bf16 v[54:57], v[178:181], v[212:215], v[54:57]
	v_mfma_f32_16x16x32_bf16 v[50:53], v[204:207], v[212:215], v[50:53]
	v_mfma_f32_16x16x32_bf16 v[38:41], v[178:181], v[220:223], v[38:41]
	v_mfma_f32_16x16x32_bf16 v[34:37], v[204:207], v[220:223], v[34:37]
	v_mfma_f32_16x16x32_bf16 v[22:25], v[178:181], v[228:231], v[22:25]
	v_mfma_f32_16x16x32_bf16 v[18:21], v[204:207], v[228:231], v[18:21]
	v_mfma_f32_16x16x32_bf16 v[6:9], v[178:181], v[236:239], v[6:9]
	v_mfma_f32_16x16x32_bf16 v[2:5], v[204:207], v[236:239], v[2:5]
	s_setprio 0
	s_setprio 2
	v_mfma_f32_16x16x32_bf16 v[54:57], v[182:185], v[216:219], v[54:57]
	v_mfma_f32_16x16x32_bf16 v[50:53], v[208:211], v[216:219], v[50:53]
	v_mfma_f32_16x16x32_bf16 v[38:41], v[182:185], v[224:227], v[38:41]
	v_mfma_f32_16x16x32_bf16 v[34:37], v[208:211], v[224:227], v[34:37]
	v_mfma_f32_16x16x32_bf16 v[22:25], v[182:185], v[232:235], v[22:25]
	v_mfma_f32_16x16x32_bf16 v[18:21], v[208:211], v[232:235], v[18:21]
	v_mfma_f32_16x16x32_bf16 v[6:9], v[182:185], v[240:243], v[6:9]
	v_mfma_f32_16x16x32_bf16 v[2:5], v[208:211], v[240:243], v[2:5]
	s_setprio 1
	s_barrier
	s_add_i32 s46, s46, 2
	s_add_u32 s0, s0, 0x100
	s_addc_u32 s1, s1, 0
	s_add_u32 s78, s78, 0x100
	s_addc_u32 s79, s79, 0
	s_cmp_gt_u32 s46, 29
	s_cbranch_scc0 .LBB0_76
	s_and_b64 vcc, exec, s[42:43]
	s_cbranch_vccz .LBB0_79
	s_barrier

; #define PG8_STAGE(bufoff, gbase, voff) do { _Pragma("unroll") for (int _i = 0; _i < 2; ++_i) \
;         __builtin_amdgcn_global_load_lds((const unsigned*)((const char*)(gbase) + (voff)[_i]), (PG8_LAS unsigned*)(lds + (bufoff) + ldsw + _i * 8192), 16, 0, 0); } while (0)
; #define PG8_LDA(dst, b, h) do { _Pragma("unroll") for (int m = 0; m < 4; ++m) _Pragma("unroll") for (int k = 0; k < 2; ++k) dst[m][k] = *(const PG8_LAS bf16x8*)(lds + PG8_SA(b, h) + aoff + m * 2048 + k * 1024); } while (0)
; #define PG8_LDB(dst, b, h) do { _Pragma("unroll") for (int n = 0; n < 2; ++n) _Pragma("unroll") for (int k = 0; k < 2; ++k) dst[n][k] = *(const PG8_LAS bf16x8*)(lds + PG8_SB(b, h) + boff + n * 2048 + k * 1024); } while (0)
; #define PG8_MMA(ai, bj, At, Bt) do { __builtin_amdgcn_s_setprio(1); _Pragma("unroll") for (int m = 0; m < 4; ++m) _Pragma("unroll") for (int n = 0; n < 2; ++n) _Pragma("unroll") for (int k = 0; k < 2; ++k) \
;         acc[ai][bj][m][n] = __builtin_amdgcn_mfma_f32_16x16x32_bf16(Bt[n][k], At[m][k], acc[ai][bj][m][n], 0, 0, 0); __builtin_amdgcn_s_setprio(0); } while (0)
; #define PG8_WAIT_V(n) asm volatile("s_waitcnt vmcnt(" #n ")" ::: "memory")
; #define PG8_BAR __builtin_amdgcn_s_barrier()
; template <class Epi, class Sched, bool ALIGN_EPI = false, bool SP2 = false>
; __device__ __forceinline__ void gemm_phase(PG8_LAS unsigned char* lds, const Gemm g, const Sched& S, const Epi& E) {
;     ...
;         for (int t = 0; t < nt; t += 2) {
;             const bool last = (t == nt - 2);
;             const char* a1 = cA + (size_t)(t + 1) * kstep;
;             const char* a2 = last ? nA : cA + (size_t)(t + 2) * kstep; const char* b2 = last ? nB : cB + (size_t)(t + 2) * kstep;
;             const char* a3 = a2 + kstep; const char* b3 = b2 + kstep;
;             if (last && has_next) S.a_ready(nxt);
;             if constexpr (SP2) {
;             PG8_LDB(B0, 0, 0); PG8_LDB(B1, 0, 1); PG8_SCHED; PG8_LDA(At, 0, 0); PG8_STAGE(PG8_SA(1, 1), a1 + hstep, voffA);
;             PG8_WAIT_V(8); PG8_WAIT_L(0); PG8_BAR; PG8_MMA(0, 0, At, B0); PG8_MMA(0, 1, At, B1); PG8_BAR; PG8_SCHED;
;             PG8_LDA(At, 0, 1); PG8_STAGE(PG8_SB(0, 0), b2, voffB); PG8_STAGE(PG8_SB(0, 1), b2 + hstep, voffB); PG8_STAGE(PG8_SA(0, 0), a2, voffA);
;             PG8_WAIT_V(8); PG8_WAIT_L(0); PG8_BAR; PG8_MMA(1, 0, At, B0); PG8_MMA(1, 1, At, B1); PG8_BAR; PG8_SCHED;
.LBB0_98:
	s_add_u32 s40, vcc_lo, 0xfff80080
	s_addc_u32 s41, vcc_hi, -1
	s_add_i32 s47, 0, 0x10000
	s_cmp_eq_u32 s46, 28
	s_cselect_b32 s59, s97, s41
	s_cselect_b32 s58, s84, s40
	s_cselect_b32 s41, s85, s79
	s_cselect_b32 s40, s95, s78
	s_add_i32 s80, 0, 0x14000
	v_add_u32_e32 v170, s47, v143
	v_add_u32_e32 v186, s80, v143
	ds_read_b128 v[156:159], v170
	ds_read_b128 v[162:165], v170 offset:1024
	ds_read_b128 v[166:169], v170 offset:2048
	ds_read_b128 v[170:173], v170 offset:3072
	ds_read_b128 v[174:177], v186
	ds_read_b128 v[178:181], v186 offset:1024
	ds_read_b128 v[182:185], v186 offset:2048
	ds_read_b128 v[204:207], v186 offset:3072
	v_lshl_add_u64 v[186:187], vcc, 0, v[152:153]
	s_add_i32 m0, s5, 0xc000
	ds_read_b128 v[208:211], v161
	ds_read_b128 v[212:215], v161 offset:1024
	ds_read_b128 v[216:219], v161 offset:2048
	ds_read_b128 v[220:223], v161 offset:3072
	ds_read_b128 v[224:227], v161 offset:4096
	ds_read_b128 v[228:231], v161 offset:5120
	ds_read_b128 v[232:235], v161 offset:6144
	ds_read_b128 v[236:239], v161 offset:7168
	global_load_lds_dwordx4 v[186:187], off
	v_lshl_add_u64 v[186:187], vcc, 0, v[154:155]
	s_add_i32 m0, s5, 0xe000
	s_nop 0
	global_load_lds_dwordx4 v[186:187], off
	s_waitcnt vmcnt(8)
	s_waitcnt lgkmcnt(0)
	s_barrier
	s_setprio 2
	v_mfma_f32_16x16x32_bf16 v[126:129], v[156:159], v[208:211], v[126:129]
	v_mfma_f32_16x16x32_bf16 v[122:125], v[166:169], v[208:211], v[122:125]
	v_mfma_f32_16x16x32_bf16 v[110:113], v[156:159], v[216:219], v[110:113]
	v_mfma_f32_16x16x32_bf16 v[106:109], v[166:169], v[216:219], v[106:109]
	v_mfma_f32_16x16x32_bf16 v[94:97], v[156:159], v[224:227], v[94:97]
	v_mfma_f32_16x16x32_bf16 v[90:93], v[166:169], v[224:227], v[90:93]
	v_mfma_f32_16x16x32_bf16 v[78:81], v[156:159], v[232:235], v[78:81]
	v_mfma_f32_16x16x32_bf16 v[74:77], v[166:169], v[232:235], v[74:77]
	s_setprio 0
	s_setprio 2
	v_mfma_f32_16x16x32_bf16 v[126:129], v[162:165], v[212:215], v[126:129]
	v_mfma_f32_16x16x32_bf16 v[122:125], v[170:173], v[212:215], v[122:125]
	v_mfma_f32_16x16x32_bf16 v[110:113], v[162:165], v[220:223], v[110:113]
	v_mfma_f32_16x16x32_bf16 v[106:109], v[170:173], v[220:223], v[106:109]
	v_mfma_f32_16x16x32_bf16 v[94:97], v[162:165], v[228:231], v[94:97]
	v_mfma_f32_16x16x32_bf16 v[90:93], v[170:173], v[228:231], v[90:93]
	v_mfma_f32_16x16x32_bf16 v[78:81], v[162:165], v[236:239], v[78:81]
	v_mfma_f32_16x16x32_bf16 v[74:77], v[170:173], v[236:239], v[74:77]
	s_setprio 0
	s_setprio 2
	v_mfma_f32_16x16x32_bf16 v[118:121], v[174:177], v[208:211], v[118:121]
	v_mfma_f32_16x16x32_bf16 v[114:117], v[182:185], v[208:211], v[114:117]
	v_mfma_f32_16x16x32_bf16 v[102:105], v[174:177], v[216:219], v[102:105]
	v_mfma_f32_16x16x32_bf16 v[98:101], v[182:185], v[216:219], v[98:101]
	v_mfma_f32_16x16x32_bf16 v[86:89], v[174:177], v[224:227], v[86:89]
	v_mfma_f32_16x16x32_bf16 v[82:85], v[182:185], v[224:227], v[82:85]
	v_mfma_f32_16x16x32_bf16 v[70:73], v[174:177], v[232:235], v[70:73]
	v_mfma_f32_16x16x32_bf16 v[66:69], v[182:185], v[232:235], v[66:69]
	s_setprio 0
	s_setprio 2
	v_mfma_f32_16x16x32_bf16 v[118:121], v[178:181], v[212:215], v[118:121]
	v_mfma_f32_16x16x32_bf16 v[114:117], v[204:207], v[212:215], v[114:117]
	v_mfma_f32_16x16x32_bf16 v[102:105], v[178:181], v[220:223], v[102:105]
	v_mfma_f32_16x16x32_bf16 v[98:101], v[204:207], v[220:223], v[98:101]
	v_mfma_f32_16x16x32_bf16 v[86:89], v[178:181], v[228:231], v[86:89]
	v_mfma_f32_16x16x32_bf16 v[82:85], v[204:207], v[228:231], v[82:85]
	v_mfma_f32_16x16x32_bf16 v[70:73], v[178:181], v[236:239], v[70:73]
	v_mfma_f32_16x16x32_bf16 v[66:69], v[204:207], v[236:239], v[66:69]
	s_setprio 1
	s_barrier
	s_add_i32 s47, s47, s4
	v_lshl_add_u64 v[186:187], s[40:41], 0, v[148:149]
	s_mov_b32 m0, s47
	ds_read_b128 v[208:211], v161 offset:16384
	ds_read_b128 v[212:215], v161 offset:17408
	ds_read_b128 v[216:219], v161 offset:18432
	ds_read_b128 v[220:223], v161 offset:19456
	ds_read_b128 v[224:227], v161 offset:20480
	ds_read_b128 v[228:231], v161 offset:21504
	ds_read_b128 v[232:235], v161 offset:22528
	ds_read_b128 v[236:239], v161 offset:23552
	global_load_lds_dwordx4 v[186:187], off
	s_add_i32 m0, s47, 0x2000
	s_add_u32 s76, s40, 0x80000
	v_lshl_add_u64 v[240:241], s[40:41], 0, v[144:145]
	s_addc_u32 s77, s41, 0
	s_add_i32 s47, s80, s4
	global_load_lds_dwordx4 v[240:241], off
	v_lshl_add_u64 v[242:243], s[76:77], 0, v[148:149]
	s_mov_b32 m0, s47
	v_lshl_add_u64 v[244:245], s[58:59], 0, v[146:147]
	global_load_lds_dwordx4 v[242:243], off
	v_lshl_add_u64 v[242:243], s[76:77], 0, v[144:145]
	s_add_i32 m0, s47, 0x2000
	s_nop 0
	global_load_lds_dwordx4 v[242:243], off
	v_lshl_add_u64 v[242:243], s[58:59], 0, v[150:151]
	s_mov_b32 m0, s5
	s_nop 0
	global_load_lds_dwordx4 v[242:243], off
	s_mov_b32 m0, s30
	s_nop 0
	global_load_lds_dwordx4 v[244:245], off
	s_waitcnt vmcnt(8)
	s_waitcnt lgkmcnt(0)
	s_barrier
; #define PG8_STAGE(bufoff, gbase, voff) do { _Pragma("unroll") for (int _i = 0; _i < 2; ++_i) \
;         __builtin_amdgcn_global_load_lds((const unsigned*)((const char*)(gbase) + (voff)[_i]), (PG8_LAS unsigned*)(lds + (bufoff) + ldsw + _i * 8192), 16, 0, 0); } while (0)
; #define PG8_LDA(dst, b, h) do { _Pragma("unroll") for (int m = 0; m < 4; ++m) _Pragma("unroll") for (int k = 0; k < 2; ++k) dst[m][k] = *(const PG8_LAS bf16x8*)(lds + PG8_SA(b, h) + aoff + m * 2048 + k * 1024); } while (0)
; #define PG8_LDB(dst, b, h) do { _Pragma("unroll") for (int n = 0; n < 2; ++n) _Pragma("unroll") for (int k = 0; k < 2; ++k) dst[n][k] = *(const PG8_LAS bf16x8*)(lds + PG8_SB(b, h) + boff + n * 2048 + k * 1024); } while (0)
; #define PG8_MMA(ai, bj, At, Bt) do { __builtin_amdgcn_s_setprio(1); _Pragma("unroll") for (int m = 0; m < 4; ++m) _Pragma("unroll") for (int n = 0; n < 2; ++n) _Pragma("unroll") for (int k = 0; k < 2; ++k) \
;         acc[ai][bj][m][n] = __builtin_amdgcn_mfma_f32_16x16x32_bf16(Bt[n][k], At[m][k], acc[ai][bj][m][n], 0, 0, 0); __builtin_amdgcn_s_setprio(0); } while (0)
; #define PG8_WAIT_V(n) asm volatile("s_waitcnt vmcnt(" #n ")" ::: "memory")
; #define PG8_WAIT_L(n) asm volatile("s_waitcnt lgkmcnt(" #n ")" ::: "memory")
; #define PG8_BAR __builtin_amdgcn_s_barrier()
; #define PG8_SCHED __builtin_amdgcn_sched_barrier(0)
; template <class Epi, class Sched, bool ALIGN_EPI = false, bool SP2 = false>
; __device__ __forceinline__ void gemm_phase(PG8_LAS unsigned char* lds, const Gemm g, const Sched& S, const Epi& E) {
;     ...
;             PG8_WAIT_V(8); PG8_WAIT_L(0); PG8_BAR; PG8_MMA(1, 0, At, B0); PG8_MMA(1, 1, At, B1); PG8_BAR; PG8_SCHED;
;             PG8_LDB(B0, 1, 0); PG8_LDB(B1, 1, 1); PG8_SCHED; PG8_LDA(At, 1, 0); PG8_STAGE(PG8_SA(0, 1), a2 + hstep, voffA);
;             PG8_WAIT_V(8); PG8_WAIT_L(0); PG8_BAR; PG8_MMA(0, 0, At, B0); PG8_MMA(0, 1, At, B1); PG8_BAR; PG8_SCHED;
	s_setprio 2
	v_mfma_f32_16x16x32_bf16 v[62:65], v[156:159], v[208:211], v[62:65]
	v_mfma_f32_16x16x32_bf16 v[58:61], v[166:169], v[208:211], v[58:61]
	v_mfma_f32_16x16x32_bf16 v[46:49], v[156:159], v[216:219], v[46:49]
	v_mfma_f32_16x16x32_bf16 v[42:45], v[166:169], v[216:219], v[42:45]
	v_mfma_f32_16x16x32_bf16 v[30:33], v[156:159], v[224:227], v[30:33]
	v_mfma_f32_16x16x32_bf16 v[26:29], v[166:169], v[224:227], v[26:29]
	v_mfma_f32_16x16x32_bf16 v[14:17], v[156:159], v[232:235], v[14:17]
	v_mfma_f32_16x16x32_bf16 v[10:13], v[166:169], v[232:235], v[10:13]
	s_setprio 0
	s_setprio 2
	v_mfma_f32_16x16x32_bf16 v[62:65], v[162:165], v[212:215], v[62:65]
	v_mfma_f32_16x16x32_bf16 v[58:61], v[170:173], v[212:215], v[58:61]
	v_mfma_f32_16x16x32_bf16 v[46:49], v[162:165], v[220:223], v[46:49]
	v_mfma_f32_16x16x32_bf16 v[42:45], v[170:173], v[220:223], v[42:45]
	v_mfma_f32_16x16x32_bf16 v[30:33], v[162:165], v[228:231], v[30:33]
	v_mfma_f32_16x16x32_bf16 v[26:29], v[170:173], v[228:231], v[26:29]
	v_mfma_f32_16x16x32_bf16 v[14:17], v[162:165], v[236:239], v[14:17]
	v_mfma_f32_16x16x32_bf16 v[10:13], v[170:173], v[236:239], v[10:13]
	s_setprio 0
	s_setprio 2
	v_mfma_f32_16x16x32_bf16 v[54:57], v[174:177], v[208:211], v[54:57]
	v_mfma_f32_16x16x32_bf16 v[50:53], v[182:185], v[208:211], v[50:53]
	v_mfma_f32_16x16x32_bf16 v[38:41], v[174:177], v[216:219], v[38:41]
	v_mfma_f32_16x16x32_bf16 v[34:37], v[182:185], v[216:219], v[34:37]
	v_mfma_f32_16x16x32_bf16 v[22:25], v[174:177], v[224:227], v[22:25]
	v_mfma_f32_16x16x32_bf16 v[18:21], v[182:185], v[224:227], v[18:21]
	v_mfma_f32_16x16x32_bf16 v[6:9], v[174:177], v[232:235], v[6:9]
	v_mfma_f32_16x16x32_bf16 v[2:5], v[182:185], v[232:235], v[2:5]
	s_setprio 0
	s_setprio 2
	v_mfma_f32_16x16x32_bf16 v[54:57], v[178:181], v[212:215], v[54:57]
	v_mfma_f32_16x16x32_bf16 v[50:53], v[204:207], v[212:215], v[50:53]
	v_mfma_f32_16x16x32_bf16 v[38:41], v[178:181], v[220:223], v[38:41]
	v_mfma_f32_16x16x32_bf16 v[34:37], v[204:207], v[220:223], v[34:37]
	v_mfma_f32_16x16x32_bf16 v[22:25], v[178:181], v[228:231], v[22:25]
	v_mfma_f32_16x16x32_bf16 v[18:21], v[204:207], v[228:231], v[18:21]
	v_mfma_f32_16x16x32_bf16 v[6:9], v[178:181], v[236:239], v[6:9]
	v_mfma_f32_16x16x32_bf16 v[2:5], v[204:207], v[236:239], v[2:5]
	s_setprio 1
	s_barrier
	s_add_i32 s47, 0, 0x18000
	s_add_i32 s76, 0, 0x1c000
	v_add_u32_e32 v170, s47, v143
	v_add_u32_e32 v203, s76, v143
	ds_read_b128 v[156:159], v170
	ds_read_b128 v[162:165], v170 offset:1024
	ds_read_b128 v[166:169], v170 offset:2048
	ds_read_b128 v[170:173], v170 offset:3072
	ds_read_b128 v[174:177], v203
	ds_read_b128 v[178:181], v203 offset:1024
	ds_read_b128 v[182:185], v203 offset:2048
	ds_read_b128 v[204:207], v203 offset:3072
	s_add_u32 s58, s58, 0x80000
	s_addc_u32 s59, s59, 0
	s_mov_b32 m0, s34
	v_lshl_add_u64 v[246:247], s[58:59], 0, v[150:151]
	ds_read_b128 v[208:211], v161 offset:32768
	ds_read_b128 v[212:215], v161 offset:33792
	ds_read_b128 v[216:219], v161 offset:34816
	ds_read_b128 v[220:223], v161 offset:35840
	ds_read_b128 v[224:227], v161 offset:36864
	ds_read_b128 v[228:231], v161 offset:37888
	ds_read_b128 v[232:235], v161 offset:38912
	ds_read_b128 v[236:239], v161 offset:39936
	global_load_lds_dwordx4 v[246:247], off
	v_lshl_add_u64 v[246:247], s[58:59], 0, v[146:147]
	s_mov_b32 m0, s57
	s_nop 0
	global_load_lds_dwordx4 v[246:247], off
	s_waitcnt vmcnt(8)
	s_waitcnt lgkmcnt(0)
	s_barrier
	s_setprio 2
	v_mfma_f32_16x16x32_bf16 v[126:129], v[156:159], v[208:211], v[126:129]
	v_mfma_f32_16x16x32_bf16 v[122:125], v[166:169], v[208:211], v[122:125]
	v_mfma_f32_16x16x32_bf16 v[110:113], v[156:159], v[216:219], v[110:113]
	v_mfma_f32_16x16x32_bf16 v[106:109], v[166:169], v[216:219], v[106:109]
	v_mfma_f32_16x16x32_bf16 v[94:97], v[156:159], v[224:227], v[94:97]
	v_mfma_f32_16x16x32_bf16 v[90:93], v[166:169], v[224:227], v[90:93]
	v_mfma_f32_16x16x32_bf16 v[78:81], v[156:159], v[232:235], v[78:81]
	v_mfma_f32_16x16x32_bf16 v[74:77], v[166:169], v[232:235], v[74:77]
	s_setprio 0
	s_setprio 2
	v_mfma_f32_16x16x32_bf16 v[126:129], v[162:165], v[212:215], v[126:129]
	v_mfma_f32_16x16x32_bf16 v[122:125], v[170:173], v[212:215], v[122:125]
	v_mfma_f32_16x16x32_bf16 v[110:113], v[162:165], v[220:223], v[110:113]
	v_mfma_f32_16x16x32_bf16 v[106:109], v[170:173], v[220:223], v[106:109]
	v_mfma_f32_16x16x32_bf16 v[94:97], v[162:165], v[228:231], v[94:97]
	v_mfma_f32_16x16x32_bf16 v[90:93], v[170:173], v[228:231], v[90:93]
	v_mfma_f32_16x16x32_bf16 v[78:81], v[162:165], v[236:239], v[78:81]
	v_mfma_f32_16x16x32_bf16 v[74:77], v[170:173], v[236:239], v[74:77]
	s_setprio 0
	s_setprio 2
	v_mfma_f32_16x16x32_bf16 v[118:121], v[174:177], v[208:211], v[118:121]
	v_mfma_f32_16x16x32_bf16 v[114:117], v[182:185], v[208:211], v[114:117]
	v_mfma_f32_16x16x32_bf16 v[102:105], v[174:177], v[216:219], v[102:105]
	v_mfma_f32_16x16x32_bf16 v[98:101], v[182:185], v[216:219], v[98:101]
	v_mfma_f32_16x16x32_bf16 v[86:89], v[174:177], v[224:227], v[86:89]
	v_mfma_f32_16x16x32_bf16 v[82:85], v[182:185], v[224:227], v[82:85]
	v_mfma_f32_16x16x32_bf16 v[70:73], v[174:177], v[232:235], v[70:73]
	v_mfma_f32_16x16x32_bf16 v[66:69], v[182:185], v[232:235], v[66:69]
	s_setprio 0
	s_setprio 2
	v_mfma_f32_16x16x32_bf16 v[118:121], v[178:181], v[212:215], v[118:121]
	v_mfma_f32_16x16x32_bf16 v[114:117], v[204:207], v[212:215], v[114:117]
	v_mfma_f32_16x16x32_bf16 v[102:105], v[178:181], v[220:223], v[102:105]
	v_mfma_f32_16x16x32_bf16 v[98:101], v[204:207], v[220:223], v[98:101]
	v_mfma_f32_16x16x32_bf16 v[86:89], v[178:181], v[228:231], v[86:89]
	v_mfma_f32_16x16x32_bf16 v[82:85], v[204:207], v[228:231], v[82:85]
	v_mfma_f32_16x16x32_bf16 v[70:73], v[178:181], v[236:239], v[70:73]
	v_mfma_f32_16x16x32_bf16 v[66:69], v[204:207], v[236:239], v[66:69]
	s_setprio 1
	s_barrier
; #define PG8_STAGE(bufoff, gbase, voff) do { _Pragma("unroll") for (int _i = 0; _i < 2; ++_i) \
;         __builtin_amdgcn_global_load_lds((const unsigned*)((const char*)(gbase) + (voff)[_i]), (PG8_LAS unsigned*)(lds + (bufoff) + ldsw + _i * 8192), 16, 0, 0); } while (0)
; #define PG8_LDA(dst, b, h) do { _Pragma("unroll") for (int m = 0; m < 4; ++m) _Pragma("unroll") for (int k = 0; k < 2; ++k) dst[m][k] = *(const PG8_LAS bf16x8*)(lds + PG8_SA(b, h) + aoff + m * 2048 + k * 1024); } while (0)
; #define PG8_MMA(ai, bj, At, Bt) do { __builtin_amdgcn_s_setprio(1); _Pragma("unroll") for (int m = 0; m < 4; ++m) _Pragma("unroll") for (int n = 0; n < 2; ++n) _Pragma("unroll") for (int k = 0; k < 2; ++k) \
;         acc[ai][bj][m][n] = __builtin_amdgcn_mfma_f32_16x16x32_bf16(Bt[n][k], At[m][k], acc[ai][bj][m][n], 0, 0, 0); __builtin_amdgcn_s_setprio(0); } while (0)
; #define PG8_WAIT_V(n) asm volatile("s_waitcnt vmcnt(" #n ")" ::: "memory")
; #define PG8_WAIT_L(n) asm volatile("s_waitcnt lgkmcnt(" #n ")" ::: "memory")
; #define PG8_BAR __builtin_amdgcn_s_barrier()
; #define PG8_SCHED __builtin_amdgcn_sched_barrier(0)
;     __device__ __forceinline__ void operator()(const f32x4 (&acc)[2][2][4][2], const Unit& u, int wr, int wc, int fr, int fq) const {
;     ...
;             for (int m = 0; m < 4; ++m) { const size_t row = (size_t)(row0 + ai * HALF + m * 16); float ss = 0.f;
; #pragma unroll
;                 for (int bj = 0; bj < 2; ++bj) { const size_t off = row * DM + col0 + bj * HALF;
;                     f32x4 v0 = acc[ai][bj][m][0] + *(const f32x4*)(base + off), v1 = acc[ai][bj][m][1] + *(const f32x4*)(base + off + 4);
; template <class Epi, class Sched, bool ALIGN_EPI = false, bool SP2 = false>
; __device__ __forceinline__ void gemm_phase(PG8_LAS unsigned char* lds, const Gemm g, const Sched& S, const Epi& E) {
;     ...
;             PG8_LDA(At, 1, 1); PG8_STAGE(PG8_SB(1, 0), b3, voffB); PG8_STAGE(PG8_SB(1, 1), b3 + hstep, voffB); PG8_STAGE(PG8_SA(1, 0), a3, voffA);
;             PG8_WAIT_V(8); PG8_WAIT_L(0); PG8_BAR; PG8_MMA(1, 0, At, B0); PG8_MMA(1, 1, At, B1); PG8_BAR; PG8_SCHED;
	s_add_i32 s47, s47, s4
	v_lshl_add_u64 v[186:187], v[186:187], 0, s[68:69]
	s_mov_b32 m0, s47
	ds_read_b128 v[208:211], v161 offset:49152
	ds_read_b128 v[212:215], v161 offset:50176
	ds_read_b128 v[216:219], v161 offset:51200
	ds_read_b128 v[220:223], v161 offset:52224
	ds_read_b128 v[224:227], v161 offset:53248
	ds_read_b128 v[228:231], v161 offset:54272
	ds_read_b128 v[232:235], v161 offset:55296
	ds_read_b128 v[236:239], v161 offset:56320
	global_load_lds_dwordx4 v[186:187], off
	s_add_i32 m0, s47, 0x2000
	s_add_u32 s40, s40, 0x80080
	v_lshl_add_u64 v[186:187], v[240:241], 0, s[68:69]
	s_addc_u32 s41, s41, 0
	s_add_i32 s47, s76, s4
	global_load_lds_dwordx4 v[186:187], off
	v_lshl_add_u64 v[186:187], s[40:41], 0, v[148:149]
	s_mov_b32 m0, s47
	s_nop 0
	global_load_lds_dwordx4 v[186:187], off
	v_lshl_add_u64 v[186:187], s[40:41], 0, v[144:145]
	s_add_i32 m0, s47, 0x2000
	s_nop 0
	global_load_lds_dwordx4 v[186:187], off
	v_lshl_add_u64 v[186:187], v[242:243], 0, s[68:69]
	s_mov_b32 m0, s67
	s_nop 0
	global_load_lds_dwordx4 v[186:187], off
	v_lshl_add_u64 v[186:187], v[244:245], 0, s[68:69]
	s_mov_b32 m0, s28
	s_nop 0
	global_load_lds_dwordx4 v[186:187], off
	s_nop 0
	s_waitcnt vmcnt(8)
	s_waitcnt lgkmcnt(0)
	s_barrier
	s_setprio 2
	v_mfma_f32_16x16x32_bf16 v[62:65], v[156:159], v[208:211], v[62:65]
	v_mfma_f32_16x16x32_bf16 v[58:61], v[166:169], v[208:211], v[58:61]
	v_mfma_f32_16x16x32_bf16 v[46:49], v[156:159], v[216:219], v[46:49]
	v_mfma_f32_16x16x32_bf16 v[42:45], v[166:169], v[216:219], v[42:45]
	v_mfma_f32_16x16x32_bf16 v[30:33], v[156:159], v[224:227], v[30:33]
	v_mfma_f32_16x16x32_bf16 v[26:29], v[166:169], v[224:227], v[26:29]
	v_mfma_f32_16x16x32_bf16 v[14:17], v[156:159], v[232:235], v[14:17]
	v_mfma_f32_16x16x32_bf16 v[10:13], v[166:169], v[232:235], v[10:13]
	s_setprio 0
	s_setprio 2
	v_mfma_f32_16x16x32_bf16 v[62:65], v[162:165], v[212:215], v[62:65]
	v_mfma_f32_16x16x32_bf16 v[58:61], v[170:173], v[212:215], v[58:61]
	v_mfma_f32_16x16x32_bf16 v[46:49], v[162:165], v[220:223], v[46:49]
	v_mfma_f32_16x16x32_bf16 v[42:45], v[170:173], v[220:223], v[42:45]
	v_mfma_f32_16x16x32_bf16 v[30:33], v[162:165], v[228:231], v[30:33]
	v_mfma_f32_16x16x32_bf16 v[26:29], v[170:173], v[228:231], v[26:29]
	v_mfma_f32_16x16x32_bf16 v[14:17], v[162:165], v[236:239], v[14:17]
	v_mfma_f32_16x16x32_bf16 v[10:13], v[170:173], v[236:239], v[10:13]
	s_setprio 0
	s_setprio 2
	v_mfma_f32_16x16x32_bf16 v[54:57], v[174:177], v[208:211], v[54:57]
	v_mfma_f32_16x16x32_bf16 v[50:53], v[182:185], v[208:211], v[50:53]
	v_mfma_f32_16x16x32_bf16 v[38:41], v[174:177], v[216:219], v[38:41]
	v_mfma_f32_16x16x32_bf16 v[34:37], v[182:185], v[216:219], v[34:37]
	v_mfma_f32_16x16x32_bf16 v[22:25], v[174:177], v[224:227], v[22:25]
	v_mfma_f32_16x16x32_bf16 v[18:21], v[182:185], v[224:227], v[18:21]
	v_mfma_f32_16x16x32_bf16 v[6:9], v[174:177], v[232:235], v[6:9]
	v_mfma_f32_16x16x32_bf16 v[2:5], v[182:185], v[232:235], v[2:5]
	s_setprio 0
	s_setprio 2
	v_mfma_f32_16x16x32_bf16 v[54:57], v[178:181], v[212:215], v[54:57]
	v_mfma_f32_16x16x32_bf16 v[50:53], v[204:207], v[212:215], v[50:53]
	v_mfma_f32_16x16x32_bf16 v[38:41], v[178:181], v[220:223], v[38:41]
	v_mfma_f32_16x16x32_bf16 v[34:37], v[204:207], v[220:223], v[34:37]
	v_mfma_f32_16x16x32_bf16 v[22:25], v[178:181], v[228:231], v[22:25]
	v_mfma_f32_16x16x32_bf16 v[18:21], v[204:207], v[228:231], v[18:21]
	v_mfma_f32_16x16x32_bf16 v[6:9], v[178:181], v[236:239], v[6:9]
	v_mfma_f32_16x16x32_bf16 v[2:5], v[204:207], v[236:239], v[2:5]
	s_setprio 1
	s_barrier
	s_add_i32 s46, s46, 2
	s_add_u32 vcc_lo, vcc_lo, 0x100
	s_addc_u32 vcc_hi, vcc_hi, 0
	s_add_u32 s78, s78, 0x100
	s_addc_u32 s79, s79, 0
	s_cmp_gt_u32 s46, 29
	s_cbranch_scc0 .LBB0_98
	v_lshl_add_u32 v156, s73, 8, v1
	v_lshl_or_b32 v157, s54, 8, v160
	v_lshl_add_u32 v157, v156, 11, v157
	v_mov_b32_e32 v247, 0
	v_lshlrev_b32_e32 v246, 2, v157
	v_lshl_add_u64 v[162:163], s[8:9], 0, v[246:247]
	v_lshlrev_b32_e32 v246, 1, v157
	v_lshl_add_u64 v[244:245], s[70:71], 0, v[246:247]
	s_mov_b32 s41, 0
	global_load_dwordx4 v[164:167], v[162:163], off
	global_load_dwordx4 v[168:171], v[162:163], off offset:16
	global_load_dwordx4 v[172:175], v[162:163], off offset:512
	global_load_dwordx4 v[176:179], v[162:163], off offset:528
	s_mov_b32 s40, 0x20000
	v_lshl_add_u64 v[246:247], v[162:163], 0, s[40:41]
	global_load_dwordx4 v[180:183], v[246:247], off
	global_load_dwordx4 v[184:187], v[246:247], off offset:16
	global_load_dwordx4 v[204:207], v[246:247], off offset:512
	global_load_dwordx4 v[208:211], v[246:247], off offset:528
	s_mov_b32 s40, 0x40000
	v_lshl_add_u64 v[246:247], v[162:163], 0, s[40:41]
	global_load_dwordx4 v[212:215], v[246:247], off
	global_load_dwordx4 v[216:219], v[246:247], off offset:16
	global_load_dwordx4 v[220:223], v[246:247], off offset:512
	global_load_dwordx4 v[224:227], v[246:247], off offset:528
	s_mov_b32 s40, 0x60000
	v_lshl_add_u64 v[246:247], v[162:163], 0, s[40:41]
	global_load_dwordx4 v[228:231], v[246:247], off
	global_load_dwordx4 v[232:235], v[246:247], off offset:16
	global_load_dwordx4 v[236:239], v[246:247], off offset:512
	global_load_dwordx4 v[240:243], v[246:247], off offset:528
	s_and_b64 vcc, exec, s[36:37]
	s_cbranch_vccz .Lx1_nobar
	s_barrier

; #define PG8_STAGE(bufoff, gbase, voff) do { _Pragma("unroll") for (int _i = 0; _i < 2; ++_i) \
;         __builtin_amdgcn_global_load_lds((const unsigned*)((const char*)(gbase) + (voff)[_i]), (PG8_LAS unsigned*)(lds + (bufoff) + ldsw + _i * 8192), 16, 0, 0); } while (0)
; #define PG8_LDA(dst, b, h) do { _Pragma("unroll") for (int m = 0; m < 4; ++m) _Pragma("unroll") for (int k = 0; k < 2; ++k) dst[m][k] = *(const PG8_LAS bf16x8*)(lds + PG8_SA(b, h) + aoff + m * 2048 + k * 1024); } while (0)
; #define PG8_LDB(dst, b, h) do { _Pragma("unroll") for (int n = 0; n < 2; ++n) _Pragma("unroll") for (int k = 0; k < 2; ++k) dst[n][k] = *(const PG8_LAS bf16x8*)(lds + PG8_SB(b, h) + boff + n * 2048 + k * 1024); } while (0)
; #define PG8_MMA(ai, bj, At, Bt) do { __builtin_amdgcn_s_setprio(1); _Pragma("unroll") for (int m = 0; m < 4; ++m) _Pragma("unroll") for (int n = 0; n < 2; ++n) _Pragma("unroll") for (int k = 0; k < 2; ++k) \
;         acc[ai][bj][m][n] = __builtin_amdgcn_mfma_f32_16x16x32_bf16(Bt[n][k], At[m][k], acc[ai][bj][m][n], 0, 0, 0); __builtin_amdgcn_s_setprio(0); } while (0)
; #define PG8_WAIT_V(n) asm volatile("s_waitcnt vmcnt(" #n ")" ::: "memory")
; #define PG8_BAR __builtin_amdgcn_s_barrier()
; template <class Epi, class Sched, bool ALIGN_EPI = false, bool SP2 = false>
; __device__ __forceinline__ void gemm_phase(PG8_LAS unsigned char* lds, const Gemm g, const Sched& S, const Epi& E) {
;     ...
;         for (int t = 0; t < nt; t += 2) {
;             const bool last = (t == nt - 2);
;             const char* a1 = cA + (size_t)(t + 1) * kstep;
;             const char* a2 = last ? nA : cA + (size_t)(t + 2) * kstep; const char* b2 = last ? nB : cB + (size_t)(t + 2) * kstep;
;             const char* a3 = a2 + kstep; const char* b3 = b2 + kstep;
;             if (last && has_next) S.a_ready(nxt);
;             if constexpr (SP2) {
;             PG8_LDB(B0, 0, 0); PG8_LDB(B1, 0, 1); PG8_SCHED; PG8_LDA(At, 0, 0); PG8_STAGE(PG8_SA(1, 1), a1 + hstep, voffA);
;             PG8_WAIT_V(8); PG8_WAIT_L(0); PG8_BAR; PG8_MMA(0, 0, At, B0); PG8_MMA(0, 1, At, B1); PG8_BAR; PG8_SCHED;
;             PG8_LDA(At, 0, 1); PG8_STAGE(PG8_SB(0, 0), b2, voffB); PG8_STAGE(PG8_SB(0, 1), b2 + hstep, voffB); PG8_STAGE(PG8_SA(0, 0), a2, voffA);
;             PG8_WAIT_V(8); PG8_WAIT_L(0); PG8_BAR; PG8_MMA(1, 0, At, B0); PG8_MMA(1, 1, At, B1); PG8_BAR; PG8_SCHED;
.LBB0_136:
	s_add_u32 s18, s58, 0xfffe0080
	s_addc_u32 s19, s59, -1
	s_add_i32 s46, 0, 0x10000
	s_cmp_eq_u32 s79, 4
	s_cselect_b32 s63, s37, s19
	s_cselect_b32 s62, s73, s18
	s_cselect_b32 s19, s11, s78
	s_cselect_b32 s18, s84, s85
	s_add_i32 s76, 0, 0x14000
	v_add_u32_e32 v172, s46, v1
	v_add_u32_e32 v203, s76, v1
	ds_read_b128 v[160:163], v172
	ds_read_b128 v[164:167], v172 offset:1024
	ds_read_b128 v[168:171], v172 offset:2048
	ds_read_b128 v[172:175], v172 offset:3072
	ds_read_b128 v[176:179], v203
	ds_read_b128 v[180:183], v203 offset:1024
	ds_read_b128 v[184:187], v203 offset:2048
	ds_read_b128 v[204:207], v203 offset:3072
	v_lshl_add_u64 v[240:241], s[58:59], 0, v[156:157]
	s_add_i32 m0, s5, 0xc000
	ds_read_b128 v[208:211], v143
	ds_read_b128 v[212:215], v143 offset:1024
	ds_read_b128 v[216:219], v143 offset:2048
	ds_read_b128 v[220:223], v143 offset:3072
	ds_read_b128 v[224:227], v143 offset:4096
	ds_read_b128 v[228:231], v143 offset:5120
	ds_read_b128 v[232:235], v143 offset:6144
	ds_read_b128 v[236:239], v143 offset:7168
	global_load_lds_dwordx4 v[240:241], off
	v_lshl_add_u64 v[240:241], s[58:59], 0, v[158:159]
	s_add_i32 m0, s5, 0xe000
	s_nop 0
	global_load_lds_dwordx4 v[240:241], off
	s_nop 0
	s_waitcnt vmcnt(8)
	s_waitcnt lgkmcnt(0)
	s_barrier
	s_setprio 2
	v_mfma_f32_16x16x32_bf16 v[126:129], v[160:163], v[208:211], v[126:129]
	v_mfma_f32_16x16x32_bf16 v[122:125], v[168:171], v[208:211], v[122:125]
	v_mfma_f32_16x16x32_bf16 v[110:113], v[160:163], v[216:219], v[110:113]
	v_mfma_f32_16x16x32_bf16 v[106:109], v[168:171], v[216:219], v[106:109]
	v_mfma_f32_16x16x32_bf16 v[94:97], v[160:163], v[224:227], v[94:97]
	v_mfma_f32_16x16x32_bf16 v[90:93], v[168:171], v[224:227], v[90:93]
	v_mfma_f32_16x16x32_bf16 v[78:81], v[160:163], v[232:235], v[78:81]
	v_mfma_f32_16x16x32_bf16 v[74:77], v[168:171], v[232:235], v[74:77]
	s_setprio 0
	s_setprio 2
	v_mfma_f32_16x16x32_bf16 v[126:129], v[164:167], v[212:215], v[126:129]
	v_mfma_f32_16x16x32_bf16 v[122:125], v[172:175], v[212:215], v[122:125]
	v_mfma_f32_16x16x32_bf16 v[110:113], v[164:167], v[220:223], v[110:113]
	v_mfma_f32_16x16x32_bf16 v[106:109], v[172:175], v[220:223], v[106:109]
	v_mfma_f32_16x16x32_bf16 v[94:97], v[164:167], v[228:231], v[94:97]
	v_mfma_f32_16x16x32_bf16 v[90:93], v[172:175], v[228:231], v[90:93]
	v_mfma_f32_16x16x32_bf16 v[78:81], v[164:167], v[236:239], v[78:81]
	v_mfma_f32_16x16x32_bf16 v[74:77], v[172:175], v[236:239], v[74:77]
	s_setprio 0
	s_setprio 2
	v_mfma_f32_16x16x32_bf16 v[118:121], v[176:179], v[208:211], v[118:121]
	v_mfma_f32_16x16x32_bf16 v[114:117], v[184:187], v[208:211], v[114:117]
	v_mfma_f32_16x16x32_bf16 v[102:105], v[176:179], v[216:219], v[102:105]
	v_mfma_f32_16x16x32_bf16 v[98:101], v[184:187], v[216:219], v[98:101]
	v_mfma_f32_16x16x32_bf16 v[86:89], v[176:179], v[224:227], v[86:89]
	v_mfma_f32_16x16x32_bf16 v[82:85], v[184:187], v[224:227], v[82:85]
	v_mfma_f32_16x16x32_bf16 v[70:73], v[176:179], v[232:235], v[70:73]
	v_mfma_f32_16x16x32_bf16 v[66:69], v[184:187], v[232:235], v[66:69]
	s_setprio 0
	s_setprio 2
	v_mfma_f32_16x16x32_bf16 v[118:121], v[180:183], v[212:215], v[118:121]
	v_mfma_f32_16x16x32_bf16 v[114:117], v[204:207], v[212:215], v[114:117]
	v_mfma_f32_16x16x32_bf16 v[102:105], v[180:183], v[220:223], v[102:105]
	v_mfma_f32_16x16x32_bf16 v[98:101], v[204:207], v[220:223], v[98:101]
	v_mfma_f32_16x16x32_bf16 v[86:89], v[180:183], v[228:231], v[86:89]
	v_mfma_f32_16x16x32_bf16 v[82:85], v[204:207], v[228:231], v[82:85]
	v_mfma_f32_16x16x32_bf16 v[70:73], v[180:183], v[236:239], v[70:73]
	v_mfma_f32_16x16x32_bf16 v[66:69], v[204:207], v[236:239], v[66:69]
	s_setprio 1
	s_barrier
	s_add_i32 s46, s46, s4
	v_lshl_add_u64 v[240:241], s[18:19], 0, v[148:149]
	s_mov_b32 m0, s46
	ds_read_b128 v[208:211], v143 offset:16384
	ds_read_b128 v[212:215], v143 offset:17408
	ds_read_b128 v[216:219], v143 offset:18432
	ds_read_b128 v[220:223], v143 offset:19456
	ds_read_b128 v[224:227], v143 offset:20480
	ds_read_b128 v[228:231], v143 offset:21504
	ds_read_b128 v[232:235], v143 offset:22528
	ds_read_b128 v[236:239], v143 offset:23552
	global_load_lds_dwordx4 v[240:241], off
	s_add_i32 m0, s46, 0x2000
	s_add_u32 s46, s18, 0x20000
	v_lshl_add_u64 v[242:243], s[18:19], 0, v[144:145]
	s_addc_u32 s47, s19, 0
	s_add_i32 s76, s76, s4
	global_load_lds_dwordx4 v[242:243], off
	v_lshl_add_u64 v[244:245], s[46:47], 0, v[148:149]
	s_mov_b32 m0, s76
	v_lshl_add_u64 v[246:247], s[62:63], 0, v[146:147]
	global_load_lds_dwordx4 v[244:245], off
	v_lshl_add_u64 v[244:245], s[46:47], 0, v[144:145]
	s_add_i32 m0, s76, 0x2000
	s_nop 0
	global_load_lds_dwordx4 v[244:245], off
	v_lshl_add_u64 v[244:245], s[62:63], 0, v[150:151]
	s_mov_b32 m0, s5
	s_nop 0
	global_load_lds_dwordx4 v[244:245], off
	s_mov_b32 m0, s28
	s_nop 0
	global_load_lds_dwordx4 v[246:247], off
	s_waitcnt vmcnt(8)
	s_waitcnt lgkmcnt(0)
	s_barrier
; #define PG8_STAGE(bufoff, gbase, voff) do { _Pragma("unroll") for (int _i = 0; _i < 2; ++_i) \
;         __builtin_amdgcn_global_load_lds((const unsigned*)((const char*)(gbase) + (voff)[_i]), (PG8_LAS unsigned*)(lds + (bufoff) + ldsw + _i * 8192), 16, 0, 0); } while (0)
; #define PG8_LDA(dst, b, h) do { _Pragma("unroll") for (int m = 0; m < 4; ++m) _Pragma("unroll") for (int k = 0; k < 2; ++k) dst[m][k] = *(const PG8_LAS bf16x8*)(lds + PG8_SA(b, h) + aoff + m * 2048 + k * 1024); } while (0)
; #define PG8_LDB(dst, b, h) do { _Pragma("unroll") for (int n = 0; n < 2; ++n) _Pragma("unroll") for (int k = 0; k < 2; ++k) dst[n][k] = *(const PG8_LAS bf16x8*)(lds + PG8_SB(b, h) + boff + n * 2048 + k * 1024); } while (0)
; #define PG8_MMA(ai, bj, At, Bt) do { __builtin_amdgcn_s_setprio(1); _Pragma("unroll") for (int m = 0; m < 4; ++m) _Pragma("unroll") for (int n = 0; n < 2; ++n) _Pragma("unroll") for (int k = 0; k < 2; ++k) \
;         acc[ai][bj][m][n] = __builtin_amdgcn_mfma_f32_16x16x32_bf16(Bt[n][k], At[m][k], acc[ai][bj][m][n], 0, 0, 0); __builtin_amdgcn_s_setprio(0); } while (0)
; #define PG8_WAIT_V(n) asm volatile("s_waitcnt vmcnt(" #n ")" ::: "memory")
; #define PG8_WAIT_L(n) asm volatile("s_waitcnt lgkmcnt(" #n ")" ::: "memory")
; #define PG8_BAR __builtin_amdgcn_s_barrier()
; #define PG8_SCHED __builtin_amdgcn_sched_barrier(0)
; template <class Epi, class Sched, bool ALIGN_EPI = false, bool SP2 = false>
; __device__ __forceinline__ void gemm_phase(PG8_LAS unsigned char* lds, const Gemm g, const Sched& S, const Epi& E) {
;     ...
;             PG8_WAIT_V(8); PG8_WAIT_L(0); PG8_BAR; PG8_MMA(1, 0, At, B0); PG8_MMA(1, 1, At, B1); PG8_BAR; PG8_SCHED;
;             PG8_LDB(B0, 1, 0); PG8_LDB(B1, 1, 1); PG8_SCHED; PG8_LDA(At, 1, 0); PG8_STAGE(PG8_SA(0, 1), a2 + hstep, voffA);
;             PG8_WAIT_V(8); PG8_WAIT_L(0); PG8_BAR; PG8_MMA(0, 0, At, B0); PG8_MMA(0, 1, At, B1); PG8_BAR; PG8_SCHED;
	s_setprio 2
	v_mfma_f32_16x16x32_bf16 v[62:65], v[160:163], v[208:211], v[62:65]
	v_mfma_f32_16x16x32_bf16 v[58:61], v[168:171], v[208:211], v[58:61]
	v_mfma_f32_16x16x32_bf16 v[46:49], v[160:163], v[216:219], v[46:49]
	v_mfma_f32_16x16x32_bf16 v[42:45], v[168:171], v[216:219], v[42:45]
	v_mfma_f32_16x16x32_bf16 v[30:33], v[160:163], v[224:227], v[30:33]
	v_mfma_f32_16x16x32_bf16 v[26:29], v[168:171], v[224:227], v[26:29]
	v_mfma_f32_16x16x32_bf16 v[14:17], v[160:163], v[232:235], v[14:17]
	v_mfma_f32_16x16x32_bf16 v[10:13], v[168:171], v[232:235], v[10:13]
	s_setprio 0
	s_setprio 2
	v_mfma_f32_16x16x32_bf16 v[62:65], v[164:167], v[212:215], v[62:65]
	v_mfma_f32_16x16x32_bf16 v[58:61], v[172:175], v[212:215], v[58:61]
	v_mfma_f32_16x16x32_bf16 v[46:49], v[164:167], v[220:223], v[46:49]
	v_mfma_f32_16x16x32_bf16 v[42:45], v[172:175], v[220:223], v[42:45]
	v_mfma_f32_16x16x32_bf16 v[30:33], v[164:167], v[228:231], v[30:33]
	v_mfma_f32_16x16x32_bf16 v[26:29], v[172:175], v[228:231], v[26:29]
	v_mfma_f32_16x16x32_bf16 v[14:17], v[164:167], v[236:239], v[14:17]
	v_mfma_f32_16x16x32_bf16 v[10:13], v[172:175], v[236:239], v[10:13]
	s_setprio 0
	s_setprio 2
	v_mfma_f32_16x16x32_bf16 v[54:57], v[176:179], v[208:211], v[54:57]
	v_mfma_f32_16x16x32_bf16 v[50:53], v[184:187], v[208:211], v[50:53]
	v_mfma_f32_16x16x32_bf16 v[38:41], v[176:179], v[216:219], v[38:41]
	v_mfma_f32_16x16x32_bf16 v[34:37], v[184:187], v[216:219], v[34:37]
	v_mfma_f32_16x16x32_bf16 v[22:25], v[176:179], v[224:227], v[22:25]
	v_mfma_f32_16x16x32_bf16 v[18:21], v[184:187], v[224:227], v[18:21]
	v_mfma_f32_16x16x32_bf16 v[6:9], v[176:179], v[232:235], v[6:9]
	v_mfma_f32_16x16x32_bf16 v[2:5], v[184:187], v[232:235], v[2:5]
	s_setprio 0
	s_setprio 2
	v_mfma_f32_16x16x32_bf16 v[54:57], v[180:183], v[212:215], v[54:57]
	v_mfma_f32_16x16x32_bf16 v[50:53], v[204:207], v[212:215], v[50:53]
	v_mfma_f32_16x16x32_bf16 v[38:41], v[180:183], v[220:223], v[38:41]
	v_mfma_f32_16x16x32_bf16 v[34:37], v[204:207], v[220:223], v[34:37]
	v_mfma_f32_16x16x32_bf16 v[22:25], v[180:183], v[228:231], v[22:25]
	v_mfma_f32_16x16x32_bf16 v[18:21], v[204:207], v[228:231], v[18:21]
	v_mfma_f32_16x16x32_bf16 v[6:9], v[180:183], v[236:239], v[6:9]
	v_mfma_f32_16x16x32_bf16 v[2:5], v[204:207], v[236:239], v[2:5]
	s_setprio 1
	s_barrier
	s_add_i32 s76, 0, 0x18000
	s_add_i32 s77, 0, 0x1c000
	v_add_u32_e32 v172, s76, v1
	v_add_u32_e32 v203, s77, v1
	ds_read_b128 v[160:163], v172
	ds_read_b128 v[164:167], v172 offset:1024
	ds_read_b128 v[168:171], v172 offset:2048
	ds_read_b128 v[172:175], v172 offset:3072
	ds_read_b128 v[176:179], v203
	ds_read_b128 v[180:183], v203 offset:1024
	ds_read_b128 v[184:187], v203 offset:2048
	ds_read_b128 v[204:207], v203 offset:3072
	s_add_u32 s46, s62, 0x20000
	s_addc_u32 s47, s63, 0
	s_mov_b32 m0, s30
	v_lshl_add_u64 v[248:249], s[46:47], 0, v[150:151]
	ds_read_b128 v[208:211], v143 offset:32768
	ds_read_b128 v[212:215], v143 offset:33792
	ds_read_b128 v[216:219], v143 offset:34816
	ds_read_b128 v[220:223], v143 offset:35840
	ds_read_b128 v[224:227], v143 offset:36864
	ds_read_b128 v[228:231], v143 offset:37888
	ds_read_b128 v[232:235], v143 offset:38912
	ds_read_b128 v[236:239], v143 offset:39936
	global_load_lds_dwordx4 v[248:249], off
	v_lshl_add_u64 v[248:249], s[46:47], 0, v[146:147]
	s_mov_b32 m0, s34
	s_nop 0
	global_load_lds_dwordx4 v[248:249], off
	s_waitcnt vmcnt(8)
	s_waitcnt lgkmcnt(0)
	s_barrier
	s_setprio 2
	v_mfma_f32_16x16x32_bf16 v[126:129], v[160:163], v[208:211], v[126:129]
	v_mfma_f32_16x16x32_bf16 v[122:125], v[168:171], v[208:211], v[122:125]
	v_mfma_f32_16x16x32_bf16 v[110:113], v[160:163], v[216:219], v[110:113]
	v_mfma_f32_16x16x32_bf16 v[106:109], v[168:171], v[216:219], v[106:109]
	v_mfma_f32_16x16x32_bf16 v[94:97], v[160:163], v[224:227], v[94:97]
	v_mfma_f32_16x16x32_bf16 v[90:93], v[168:171], v[224:227], v[90:93]
	v_mfma_f32_16x16x32_bf16 v[78:81], v[160:163], v[232:235], v[78:81]
	v_mfma_f32_16x16x32_bf16 v[74:77], v[168:171], v[232:235], v[74:77]
	s_setprio 0
	s_setprio 2
	v_mfma_f32_16x16x32_bf16 v[126:129], v[164:167], v[212:215], v[126:129]
	v_mfma_f32_16x16x32_bf16 v[122:125], v[172:175], v[212:215], v[122:125]
	v_mfma_f32_16x16x32_bf16 v[110:113], v[164:167], v[220:223], v[110:113]
	v_mfma_f32_16x16x32_bf16 v[106:109], v[172:175], v[220:223], v[106:109]
	v_mfma_f32_16x16x32_bf16 v[94:97], v[164:167], v[228:231], v[94:97]
	v_mfma_f32_16x16x32_bf16 v[90:93], v[172:175], v[228:231], v[90:93]
	v_mfma_f32_16x16x32_bf16 v[78:81], v[164:167], v[236:239], v[78:81]
	v_mfma_f32_16x16x32_bf16 v[74:77], v[172:175], v[236:239], v[74:77]
	s_setprio 0
	s_setprio 2
	v_mfma_f32_16x16x32_bf16 v[118:121], v[176:179], v[208:211], v[118:121]
	v_mfma_f32_16x16x32_bf16 v[114:117], v[184:187], v[208:211], v[114:117]
	v_mfma_f32_16x16x32_bf16 v[102:105], v[176:179], v[216:219], v[102:105]
	v_mfma_f32_16x16x32_bf16 v[98:101], v[184:187], v[216:219], v[98:101]
	v_mfma_f32_16x16x32_bf16 v[86:89], v[176:179], v[224:227], v[86:89]
	v_mfma_f32_16x16x32_bf16 v[82:85], v[184:187], v[224:227], v[82:85]
	v_mfma_f32_16x16x32_bf16 v[70:73], v[176:179], v[232:235], v[70:73]
	v_mfma_f32_16x16x32_bf16 v[66:69], v[184:187], v[232:235], v[66:69]
	s_setprio 0
	s_setprio 2
	v_mfma_f32_16x16x32_bf16 v[118:121], v[180:183], v[212:215], v[118:121]
	v_mfma_f32_16x16x32_bf16 v[114:117], v[204:207], v[212:215], v[114:117]
	v_mfma_f32_16x16x32_bf16 v[102:105], v[180:183], v[220:223], v[102:105]
	v_mfma_f32_16x16x32_bf16 v[98:101], v[204:207], v[220:223], v[98:101]
	v_mfma_f32_16x16x32_bf16 v[86:89], v[180:183], v[228:231], v[86:89]
	v_mfma_f32_16x16x32_bf16 v[82:85], v[204:207], v[228:231], v[82:85]
	v_mfma_f32_16x16x32_bf16 v[70:73], v[180:183], v[236:239], v[70:73]
	v_mfma_f32_16x16x32_bf16 v[66:69], v[204:207], v[236:239], v[66:69]
	s_setprio 1
	s_barrier
; #define PG8_STAGE(bufoff, gbase, voff) do { _Pragma("unroll") for (int _i = 0; _i < 2; ++_i) \
;         __builtin_amdgcn_global_load_lds((const unsigned*)((const char*)(gbase) + (voff)[_i]), (PG8_LAS unsigned*)(lds + (bufoff) + ldsw + _i * 8192), 16, 0, 0); } while (0)
; #define PG8_LDA(dst, b, h) do { _Pragma("unroll") for (int m = 0; m < 4; ++m) _Pragma("unroll") for (int k = 0; k < 2; ++k) dst[m][k] = *(const PG8_LAS bf16x8*)(lds + PG8_SA(b, h) + aoff + m * 2048 + k * 1024); } while (0)
; #define PG8_MMA(ai, bj, At, Bt) do { __builtin_amdgcn_s_setprio(1); _Pragma("unroll") for (int m = 0; m < 4; ++m) _Pragma("unroll") for (int n = 0; n < 2; ++n) _Pragma("unroll") for (int k = 0; k < 2; ++k) \
;         acc[ai][bj][m][n] = __builtin_amdgcn_mfma_f32_16x16x32_bf16(Bt[n][k], At[m][k], acc[ai][bj][m][n], 0, 0, 0); __builtin_amdgcn_s_setprio(0); } while (0)
; #define PG8_WAIT_V(n) asm volatile("s_waitcnt vmcnt(" #n ")" ::: "memory")
; #define PG8_WAIT_L(n) asm volatile("s_waitcnt lgkmcnt(" #n ")" ::: "memory")
; #define PG8_BAR __builtin_amdgcn_s_barrier()
; #define PG8_SCHED __builtin_amdgcn_sched_barrier(0)
;     __device__ __forceinline__ void operator()(const f32x4 (&acc)[2][2][4][2], const Unit& u, int wr, int wc, int fr, int fq) const {
;         const int row0 = u.pm * BM + wr * 64 + fr, col0 = u.pn * BM + wc * 32 + 8 * fq;
;         const int tidn = (wr * 4 + wc) * 64 + fq * 16 + fr;
;         const u32x4* gp = (const u32x4*)G8 + (size_t)(u.pm * 16 + gsel + u.pn) * 8 * 512 + tidn;
;         u32x4* mp = M1 + (size_t)(u.pm * 8 + u.pn) * 16 * 512 + tidn;
;         constexpr float K255 = 1.0f / 255.0f;
; #pragma unroll
;         for (int ai = 0; ai < 2; ++ai)
; #pragma unroll
;             for (int m = 0; m < 4; ++m) { const size_t row = (size_t)(row0 + ai * HALF + m * 16);
;                 const u32x4 gw = gp[(ai * 4 + m) * 512];
; template <class Epi, class Sched, bool ALIGN_EPI = false, bool SP2 = false>
; __device__ __forceinline__ void gemm_phase(PG8_LAS unsigned char* lds, const Gemm g, const Sched& S, const Epi& E) {
;     ...
;             PG8_LDA(At, 1, 1); PG8_STAGE(PG8_SB(1, 0), b3, voffB); PG8_STAGE(PG8_SB(1, 1), b3 + hstep, voffB); PG8_STAGE(PG8_SA(1, 0), a3, voffA);
;             PG8_WAIT_V(8); PG8_WAIT_L(0); PG8_BAR; PG8_MMA(1, 0, At, B0); PG8_MMA(1, 1, At, B1); PG8_BAR; PG8_SCHED;
	s_add_i32 s46, s76, s4
	v_lshl_add_u64 v[240:241], v[240:241], 0, s[68:69]
	s_mov_b32 m0, s46
	ds_read_b128 v[208:211], v143 offset:49152
	ds_read_b128 v[212:215], v143 offset:50176
	ds_read_b128 v[216:219], v143 offset:51200
	ds_read_b128 v[220:223], v143 offset:52224
	ds_read_b128 v[224:227], v143 offset:53248
	ds_read_b128 v[228:231], v143 offset:54272
	ds_read_b128 v[232:235], v143 offset:55296
	ds_read_b128 v[236:239], v143 offset:56320
	global_load_lds_dwordx4 v[240:241], off
	s_add_i32 m0, s46, 0x2000
	s_add_u32 s18, s18, 0x20080
	v_lshl_add_u64 v[240:241], v[242:243], 0, s[68:69]
	s_addc_u32 s19, s19, 0
	s_add_i32 s46, s77, s4
	global_load_lds_dwordx4 v[240:241], off
	v_lshl_add_u64 v[240:241], s[18:19], 0, v[148:149]
	s_mov_b32 m0, s46
	s_nop 0
	global_load_lds_dwordx4 v[240:241], off
	v_lshl_add_u64 v[240:241], s[18:19], 0, v[144:145]
	s_add_i32 m0, s46, 0x2000
	s_nop 0
	global_load_lds_dwordx4 v[240:241], off
	v_lshl_add_u64 v[240:241], v[244:245], 0, s[68:69]
	s_mov_b32 m0, s54
	s_nop 0
	global_load_lds_dwordx4 v[240:241], off
	v_lshl_add_u64 v[240:241], v[246:247], 0, s[68:69]
	s_mov_b32 m0, s57
	s_nop 0
	global_load_lds_dwordx4 v[240:241], off
	s_nop 0
	s_waitcnt vmcnt(8)
	s_waitcnt lgkmcnt(0)
	s_barrier
	s_setprio 2
	v_mfma_f32_16x16x32_bf16 v[62:65], v[160:163], v[208:211], v[62:65]
	v_mfma_f32_16x16x32_bf16 v[58:61], v[168:171], v[208:211], v[58:61]
	v_mfma_f32_16x16x32_bf16 v[46:49], v[160:163], v[216:219], v[46:49]
	v_mfma_f32_16x16x32_bf16 v[42:45], v[168:171], v[216:219], v[42:45]
	v_mfma_f32_16x16x32_bf16 v[30:33], v[160:163], v[224:227], v[30:33]
	v_mfma_f32_16x16x32_bf16 v[26:29], v[168:171], v[224:227], v[26:29]
	v_mfma_f32_16x16x32_bf16 v[14:17], v[160:163], v[232:235], v[14:17]
	v_mfma_f32_16x16x32_bf16 v[10:13], v[168:171], v[232:235], v[10:13]
	s_setprio 0
	s_setprio 2
	v_mfma_f32_16x16x32_bf16 v[62:65], v[164:167], v[212:215], v[62:65]
	v_mfma_f32_16x16x32_bf16 v[58:61], v[172:175], v[212:215], v[58:61]
	v_mfma_f32_16x16x32_bf16 v[46:49], v[164:167], v[220:223], v[46:49]
	v_mfma_f32_16x16x32_bf16 v[42:45], v[172:175], v[220:223], v[42:45]
	v_mfma_f32_16x16x32_bf16 v[30:33], v[164:167], v[228:231], v[30:33]
	v_mfma_f32_16x16x32_bf16 v[26:29], v[172:175], v[228:231], v[26:29]
	v_mfma_f32_16x16x32_bf16 v[14:17], v[164:167], v[236:239], v[14:17]
	v_mfma_f32_16x16x32_bf16 v[10:13], v[172:175], v[236:239], v[10:13]
	s_setprio 0
	s_setprio 2
	v_mfma_f32_16x16x32_bf16 v[54:57], v[176:179], v[208:211], v[54:57]
	v_mfma_f32_16x16x32_bf16 v[50:53], v[184:187], v[208:211], v[50:53]
	v_mfma_f32_16x16x32_bf16 v[38:41], v[176:179], v[216:219], v[38:41]
	v_mfma_f32_16x16x32_bf16 v[34:37], v[184:187], v[216:219], v[34:37]
	v_mfma_f32_16x16x32_bf16 v[22:25], v[176:179], v[224:227], v[22:25]
	v_mfma_f32_16x16x32_bf16 v[18:21], v[184:187], v[224:227], v[18:21]
	v_mfma_f32_16x16x32_bf16 v[6:9], v[176:179], v[232:235], v[6:9]
	v_mfma_f32_16x16x32_bf16 v[2:5], v[184:187], v[232:235], v[2:5]
	s_setprio 0
	s_setprio 2
	v_mfma_f32_16x16x32_bf16 v[54:57], v[180:183], v[212:215], v[54:57]
	v_mfma_f32_16x16x32_bf16 v[50:53], v[204:207], v[212:215], v[50:53]
	v_mfma_f32_16x16x32_bf16 v[38:41], v[180:183], v[220:223], v[38:41]
	v_mfma_f32_16x16x32_bf16 v[34:37], v[204:207], v[220:223], v[34:37]
	v_mfma_f32_16x16x32_bf16 v[22:25], v[180:183], v[228:231], v[22:25]
	v_mfma_f32_16x16x32_bf16 v[18:21], v[204:207], v[228:231], v[18:21]
	v_mfma_f32_16x16x32_bf16 v[6:9], v[180:183], v[236:239], v[6:9]
	v_mfma_f32_16x16x32_bf16 v[2:5], v[204:207], v[236:239], v[2:5]
	s_setprio 1
	s_barrier
	s_add_i32 s79, s79, 2
	s_add_u32 s58, s58, 0x100
	s_addc_u32 s59, s59, 0
	s_add_u32 s85, s85, 0x100
	s_addc_u32 s78, s78, 0
	s_cmp_gt_u32 s79, 5
	s_cbranch_scc0 .LBB0_136
	s_lshl_b32 s11, s67, 4
	s_add_i32 s18, s11, s86
	s_ashr_i32 s19, s18, 31
	s_lshl_b64 s[46:47], s[18:19], 16
	v_lshl_add_u64 v[162:163], v[152:153], 0, s[46:47]
	s_lshl_b32 s11, s67, 3
	s_sub_i32 s18, s18, s11
	s_ashr_i32 s19, s18, 31
	s_lshl_b64 s[18:19], s[18:19], 17
	v_lshl_add_u64 v[160:161], v[154:155], 0, s[18:19]
	s_mov_b32 s47, 0
	global_load_dwordx4 v[168:171], v[162:163], off
	s_mov_b32 s46, 0x2000
	v_lshl_add_u64 v[164:165], v[162:163], 0, s[46:47]
	global_load_dwordx4 v[172:175], v[164:165], off
	s_mov_b32 s46, 0x4000
	v_lshl_add_u64 v[164:165], v[162:163], 0, s[46:47]
	global_load_dwordx4 v[176:179], v[164:165], off
	s_mov_b32 s46, 0x6000
	v_lshl_add_u64 v[164:165], v[162:163], 0, s[46:47]
	global_load_dwordx4 v[180:183], v[164:165], off
	s_mov_b32 s46, 0x8000
	v_lshl_add_u64 v[164:165], v[162:163], 0, s[46:47]
	global_load_dwordx4 v[184:187], v[164:165], off
	s_mov_b32 s46, 0xa000
	v_lshl_add_u64 v[164:165], v[162:163], 0, s[46:47]
	global_load_dwordx4 v[204:207], v[164:165], off
	s_mov_b32 s46, 0xc000
	v_lshl_add_u64 v[164:165], v[162:163], 0, s[46:47]
	global_load_dwordx4 v[208:211], v[164:165], off
	s_mov_b32 s46, 0xe000
	v_lshl_add_u64 v[164:165], v[162:163], 0, s[46:47]
	global_load_dwordx4 v[212:215], v[164:165], off
	s_and_b64 vcc, exec, s[8:9]
	s_cbranch_vccz .Lg0_nobar
	s_barrier

; #define PG8_STAGE(bufoff, gbase, voff) do { _Pragma("unroll") for (int _i = 0; _i < 2; ++_i) \
;         __builtin_amdgcn_global_load_lds((const unsigned*)((const char*)(gbase) + (voff)[_i]), (PG8_LAS unsigned*)(lds + (bufoff) + ldsw + _i * 8192), 16, 0, 0); } while (0)
; #define PG8_LDA(dst, b, h) do { _Pragma("unroll") for (int m = 0; m < 4; ++m) _Pragma("unroll") for (int k = 0; k < 2; ++k) dst[m][k] = *(const PG8_LAS bf16x8*)(lds + PG8_SA(b, h) + aoff + m * 2048 + k * 1024); } while (0)
; #define PG8_LDB(dst, b, h) do { _Pragma("unroll") for (int n = 0; n < 2; ++n) _Pragma("unroll") for (int k = 0; k < 2; ++k) dst[n][k] = *(const PG8_LAS bf16x8*)(lds + PG8_SB(b, h) + boff + n * 2048 + k * 1024); } while (0)
; #define PG8_MMA(ai, bj, At, Bt) do { __builtin_amdgcn_s_setprio(1); _Pragma("unroll") for (int m = 0; m < 4; ++m) _Pragma("unroll") for (int n = 0; n < 2; ++n) _Pragma("unroll") for (int k = 0; k < 2; ++k) \
;         acc[ai][bj][m][n] = __builtin_amdgcn_mfma_f32_16x16x32_bf16(Bt[n][k], At[m][k], acc[ai][bj][m][n], 0, 0, 0); __builtin_amdgcn_s_setprio(0); } while (0)
; #define PG8_WAIT_V(n) asm volatile("s_waitcnt vmcnt(" #n ")" ::: "memory")
; #define PG8_BAR __builtin_amdgcn_s_barrier()
; template <class Epi, class Sched, bool ALIGN_EPI = false, bool SP2 = false>
; __device__ __forceinline__ void gemm_phase(PG8_LAS unsigned char* lds, const Gemm g, const Sched& S, const Epi& E) {
;     ...
;         for (int t = 0; t < nt; t += 2) {
;             const bool last = (t == nt - 2);
;             const char* a1 = cA + (size_t)(t + 1) * kstep;
;             const char* a2 = last ? nA : cA + (size_t)(t + 2) * kstep; const char* b2 = last ? nB : cB + (size_t)(t + 2) * kstep;
;             const char* a3 = a2 + kstep; const char* b3 = b2 + kstep;
;             if (last && has_next) S.a_ready(nxt);
;             if constexpr (SP2) {
;             PG8_LDB(B0, 0, 0); PG8_LDB(B1, 0, 1); PG8_SCHED; PG8_LDA(At, 0, 0); PG8_STAGE(PG8_SA(1, 1), a1 + hstep, voffA);
;             PG8_WAIT_V(8); PG8_WAIT_L(0); PG8_BAR; PG8_MMA(0, 0, At, B0); PG8_MMA(0, 1, At, B1); PG8_BAR; PG8_SCHED;
;             PG8_LDA(At, 0, 1); PG8_STAGE(PG8_SB(0, 0), b2, voffB); PG8_STAGE(PG8_SB(0, 1), b2 + hstep, voffB); PG8_STAGE(PG8_SA(0, 0), a2, voffA);
;             PG8_WAIT_V(8); PG8_WAIT_L(0); PG8_BAR; PG8_MMA(1, 0, At, B0); PG8_MMA(1, 1, At, B1); PG8_BAR; PG8_SCHED;
.LBB0_160:
	s_add_u32 s42, s36, 0x100
	s_addc_u32 s43, s37, 0
	s_add_i32 s47, 0, 0x10000
	s_cmp_eq_u32 s46, 20
	s_cselect_b32 s45, s1, s43
	s_cselect_b32 s44, s0, s42
	s_cselect_b32 s19, s7, s73
	s_cselect_b32 s18, s6, s60
	s_add_i32 s76, 0, 0x14000
	v_add_u32_e32 v174, s47, v143
	v_add_u32_e32 v186, s76, v143
	ds_read_b128 v[160:163], v174
	ds_read_b128 v[164:167], v174 offset:1024
	ds_read_b128 v[170:173], v174 offset:2048
	ds_read_b128 v[174:177], v174 offset:3072
	ds_read_b128 v[178:181], v186
	ds_read_b128 v[182:185], v186 offset:1024
	ds_read_b128 v[204:207], v186 offset:2048
	ds_read_b128 v[208:211], v186 offset:3072
	v_lshl_add_u64 v[186:187], s[36:37], 0, v[156:157]
	s_add_i32 m0, s54, 0xc000
	ds_read_b128 v[212:215], v169
	ds_read_b128 v[216:219], v169 offset:1024
	ds_read_b128 v[220:223], v169 offset:2048
	ds_read_b128 v[224:227], v169 offset:3072
	ds_read_b128 v[228:231], v169 offset:4096
	ds_read_b128 v[232:235], v169 offset:5120
	ds_read_b128 v[236:239], v169 offset:6144
	ds_read_b128 v[240:243], v169 offset:7168
	global_load_lds_dwordx4 v[186:187], off
	v_lshl_add_u64 v[186:187], s[36:37], 0, v[158:159]
	s_add_i32 m0, s54, 0xe000
	s_nop 0
	global_load_lds_dwordx4 v[186:187], off
	s_waitcnt vmcnt(8)
	s_waitcnt lgkmcnt(0)
	s_barrier
	s_setprio 2
	v_mfma_f32_16x16x32_bf16 v[126:129], v[160:163], v[212:215], v[126:129]
	v_mfma_f32_16x16x32_bf16 v[122:125], v[170:173], v[212:215], v[122:125]
	v_mfma_f32_16x16x32_bf16 v[110:113], v[160:163], v[220:223], v[110:113]
	v_mfma_f32_16x16x32_bf16 v[106:109], v[170:173], v[220:223], v[106:109]
	v_mfma_f32_16x16x32_bf16 v[94:97], v[160:163], v[228:231], v[94:97]
	v_mfma_f32_16x16x32_bf16 v[90:93], v[170:173], v[228:231], v[90:93]
	v_mfma_f32_16x16x32_bf16 v[78:81], v[160:163], v[236:239], v[78:81]
	v_mfma_f32_16x16x32_bf16 v[74:77], v[170:173], v[236:239], v[74:77]
	s_setprio 0
	s_setprio 2
	v_mfma_f32_16x16x32_bf16 v[126:129], v[164:167], v[216:219], v[126:129]
	v_mfma_f32_16x16x32_bf16 v[122:125], v[174:177], v[216:219], v[122:125]
	v_mfma_f32_16x16x32_bf16 v[110:113], v[164:167], v[224:227], v[110:113]
	v_mfma_f32_16x16x32_bf16 v[106:109], v[174:177], v[224:227], v[106:109]
	v_mfma_f32_16x16x32_bf16 v[94:97], v[164:167], v[232:235], v[94:97]
	v_mfma_f32_16x16x32_bf16 v[90:93], v[174:177], v[232:235], v[90:93]
	v_mfma_f32_16x16x32_bf16 v[78:81], v[164:167], v[240:243], v[78:81]
	v_mfma_f32_16x16x32_bf16 v[74:77], v[174:177], v[240:243], v[74:77]
	s_setprio 0
	s_setprio 2
	v_mfma_f32_16x16x32_bf16 v[118:121], v[178:181], v[212:215], v[118:121]
	v_mfma_f32_16x16x32_bf16 v[114:117], v[204:207], v[212:215], v[114:117]
	v_mfma_f32_16x16x32_bf16 v[102:105], v[178:181], v[220:223], v[102:105]
	v_mfma_f32_16x16x32_bf16 v[98:101], v[204:207], v[220:223], v[98:101]
	v_mfma_f32_16x16x32_bf16 v[86:89], v[178:181], v[228:231], v[86:89]
	v_mfma_f32_16x16x32_bf16 v[82:85], v[204:207], v[228:231], v[82:85]
	v_mfma_f32_16x16x32_bf16 v[70:73], v[178:181], v[236:239], v[70:73]
	v_mfma_f32_16x16x32_bf16 v[66:69], v[204:207], v[236:239], v[66:69]
	s_setprio 0
	s_setprio 2
	v_mfma_f32_16x16x32_bf16 v[118:121], v[182:185], v[216:219], v[118:121]
	v_mfma_f32_16x16x32_bf16 v[114:117], v[208:211], v[216:219], v[114:117]
	v_mfma_f32_16x16x32_bf16 v[102:105], v[182:185], v[224:227], v[102:105]
	v_mfma_f32_16x16x32_bf16 v[98:101], v[208:211], v[224:227], v[98:101]
	v_mfma_f32_16x16x32_bf16 v[86:89], v[182:185], v[232:235], v[86:89]
	v_mfma_f32_16x16x32_bf16 v[82:85], v[208:211], v[232:235], v[82:85]
	v_mfma_f32_16x16x32_bf16 v[70:73], v[182:185], v[240:243], v[70:73]
	v_mfma_f32_16x16x32_bf16 v[66:69], v[208:211], v[240:243], v[66:69]
	s_setprio 1
	s_barrier
	s_add_i32 s36, s47, s4
	v_lshl_add_u64 v[186:187], s[18:19], 0, v[148:149]
	s_mov_b32 m0, s36
	ds_read_b128 v[212:215], v169 offset:16384
	ds_read_b128 v[216:219], v169 offset:17408
	ds_read_b128 v[220:223], v169 offset:18432
	ds_read_b128 v[224:227], v169 offset:19456
	ds_read_b128 v[228:231], v169 offset:20480
	ds_read_b128 v[232:235], v169 offset:21504
	ds_read_b128 v[236:239], v169 offset:22528
	ds_read_b128 v[240:243], v169 offset:23552
	global_load_lds_dwordx4 v[186:187], off
	s_add_i32 m0, s36, 0x2000
	s_add_u32 s36, s18, 0x60000
	v_lshl_add_u64 v[244:245], s[18:19], 0, v[144:145]
	s_addc_u32 s37, s19, 0
	s_add_i32 s47, s76, s4
	global_load_lds_dwordx4 v[244:245], off
	v_lshl_add_u64 v[246:247], s[36:37], 0, v[148:149]
	s_mov_b32 m0, s47
	v_lshl_add_u64 v[248:249], s[44:45], 0, v[146:147]
	global_load_lds_dwordx4 v[246:247], off
	v_lshl_add_u64 v[246:247], s[36:37], 0, v[144:145]
	s_add_i32 m0, s47, 0x2000
	s_nop 0
	global_load_lds_dwordx4 v[246:247], off
	v_lshl_add_u64 v[246:247], s[44:45], 0, v[150:151]
	s_mov_b32 m0, s54
	s_nop 0
	global_load_lds_dwordx4 v[246:247], off
	s_mov_b32 m0, s57
	s_nop 0
	global_load_lds_dwordx4 v[248:249], off
	s_waitcnt vmcnt(8)
	s_waitcnt lgkmcnt(0)
	s_barrier
; #define PG8_STAGE(bufoff, gbase, voff) do { _Pragma("unroll") for (int _i = 0; _i < 2; ++_i) \
;         __builtin_amdgcn_global_load_lds((const unsigned*)((const char*)(gbase) + (voff)[_i]), (PG8_LAS unsigned*)(lds + (bufoff) + ldsw + _i * 8192), 16, 0, 0); } while (0)
; #define PG8_LDA(dst, b, h) do { _Pragma("unroll") for (int m = 0; m < 4; ++m) _Pragma("unroll") for (int k = 0; k < 2; ++k) dst[m][k] = *(const PG8_LAS bf16x8*)(lds + PG8_SA(b, h) + aoff + m * 2048 + k * 1024); } while (0)
; #define PG8_LDB(dst, b, h) do { _Pragma("unroll") for (int n = 0; n < 2; ++n) _Pragma("unroll") for (int k = 0; k < 2; ++k) dst[n][k] = *(const PG8_LAS bf16x8*)(lds + PG8_SB(b, h) + boff + n * 2048 + k * 1024); } while (0)
; #define PG8_MMA(ai, bj, At, Bt) do { __builtin_amdgcn_s_setprio(1); _Pragma("unroll") for (int m = 0; m < 4; ++m) _Pragma("unroll") for (int n = 0; n < 2; ++n) _Pragma("unroll") for (int k = 0; k < 2; ++k) \
;         acc[ai][bj][m][n] = __builtin_amdgcn_mfma_f32_16x16x32_bf16(Bt[n][k], At[m][k], acc[ai][bj][m][n], 0, 0, 0); __builtin_amdgcn_s_setprio(0); } while (0)
; #define PG8_WAIT_V(n) asm volatile("s_waitcnt vmcnt(" #n ")" ::: "memory")
; #define PG8_WAIT_L(n) asm volatile("s_waitcnt lgkmcnt(" #n ")" ::: "memory")
; #define PG8_BAR __builtin_amdgcn_s_barrier()
; #define PG8_SCHED __builtin_amdgcn_sched_barrier(0)
; template <class Epi, class Sched, bool ALIGN_EPI = false, bool SP2 = false>
; __device__ __forceinline__ void gemm_phase(PG8_LAS unsigned char* lds, const Gemm g, const Sched& S, const Epi& E) {
;     ...
;             PG8_WAIT_V(8); PG8_WAIT_L(0); PG8_BAR; PG8_MMA(1, 0, At, B0); PG8_MMA(1, 1, At, B1); PG8_BAR; PG8_SCHED;
;             PG8_LDB(B0, 1, 0); PG8_LDB(B1, 1, 1); PG8_SCHED; PG8_LDA(At, 1, 0); PG8_STAGE(PG8_SA(0, 1), a2 + hstep, voffA);
;             PG8_WAIT_V(8); PG8_WAIT_L(0); PG8_BAR; PG8_MMA(0, 0, At, B0); PG8_MMA(0, 1, At, B1); PG8_BAR; PG8_SCHED;
	s_setprio 2
	v_mfma_f32_16x16x32_bf16 v[62:65], v[160:163], v[212:215], v[62:65]
	v_mfma_f32_16x16x32_bf16 v[58:61], v[170:173], v[212:215], v[58:61]
	v_mfma_f32_16x16x32_bf16 v[46:49], v[160:163], v[220:223], v[46:49]
	v_mfma_f32_16x16x32_bf16 v[42:45], v[170:173], v[220:223], v[42:45]
	v_mfma_f32_16x16x32_bf16 v[30:33], v[160:163], v[228:231], v[30:33]
	v_mfma_f32_16x16x32_bf16 v[26:29], v[170:173], v[228:231], v[26:29]
	v_mfma_f32_16x16x32_bf16 v[14:17], v[160:163], v[236:239], v[14:17]
	v_mfma_f32_16x16x32_bf16 v[10:13], v[170:173], v[236:239], v[10:13]
	s_setprio 0
	s_setprio 2
	v_mfma_f32_16x16x32_bf16 v[62:65], v[164:167], v[216:219], v[62:65]
	v_mfma_f32_16x16x32_bf16 v[58:61], v[174:177], v[216:219], v[58:61]
	v_mfma_f32_16x16x32_bf16 v[46:49], v[164:167], v[224:227], v[46:49]
	v_mfma_f32_16x16x32_bf16 v[42:45], v[174:177], v[224:227], v[42:45]
	v_mfma_f32_16x16x32_bf16 v[30:33], v[164:167], v[232:235], v[30:33]
	v_mfma_f32_16x16x32_bf16 v[26:29], v[174:177], v[232:235], v[26:29]
	v_mfma_f32_16x16x32_bf16 v[14:17], v[164:167], v[240:243], v[14:17]
	v_mfma_f32_16x16x32_bf16 v[10:13], v[174:177], v[240:243], v[10:13]
	s_setprio 0
	s_setprio 2
	v_mfma_f32_16x16x32_bf16 v[54:57], v[178:181], v[212:215], v[54:57]
	v_mfma_f32_16x16x32_bf16 v[50:53], v[204:207], v[212:215], v[50:53]
	v_mfma_f32_16x16x32_bf16 v[38:41], v[178:181], v[220:223], v[38:41]
	v_mfma_f32_16x16x32_bf16 v[34:37], v[204:207], v[220:223], v[34:37]
	v_mfma_f32_16x16x32_bf16 v[22:25], v[178:181], v[228:231], v[22:25]
	v_mfma_f32_16x16x32_bf16 v[18:21], v[204:207], v[228:231], v[18:21]
	v_mfma_f32_16x16x32_bf16 v[6:9], v[178:181], v[236:239], v[6:9]
	v_mfma_f32_16x16x32_bf16 v[2:5], v[204:207], v[236:239], v[2:5]
	s_setprio 0
	s_setprio 2
	v_mfma_f32_16x16x32_bf16 v[54:57], v[182:185], v[216:219], v[54:57]
	v_mfma_f32_16x16x32_bf16 v[50:53], v[208:211], v[216:219], v[50:53]
	v_mfma_f32_16x16x32_bf16 v[38:41], v[182:185], v[224:227], v[38:41]
	v_mfma_f32_16x16x32_bf16 v[34:37], v[208:211], v[224:227], v[34:37]
	v_mfma_f32_16x16x32_bf16 v[22:25], v[182:185], v[232:235], v[22:25]
	v_mfma_f32_16x16x32_bf16 v[18:21], v[208:211], v[232:235], v[18:21]
	v_mfma_f32_16x16x32_bf16 v[6:9], v[182:185], v[240:243], v[6:9]
	v_mfma_f32_16x16x32_bf16 v[2:5], v[208:211], v[240:243], v[2:5]
	s_setprio 1
	s_barrier
	s_add_i32 s47, 0, 0x18000
	s_add_i32 s76, 0, 0x1c000
	v_add_u32_e32 v174, s47, v143
	v_add_u32_e32 v203, s76, v143
	ds_read_b128 v[160:163], v174
	ds_read_b128 v[164:167], v174 offset:1024
	ds_read_b128 v[170:173], v174 offset:2048
	ds_read_b128 v[174:177], v174 offset:3072
	ds_read_b128 v[178:181], v203
	ds_read_b128 v[182:185], v203 offset:1024
	ds_read_b128 v[204:207], v203 offset:2048
	ds_read_b128 v[208:211], v203 offset:3072
	s_add_u32 s36, s44, 0x60000
	s_addc_u32 s37, s45, 0
	s_mov_b32 m0, s58
	v_lshl_add_u64 v[250:251], s[36:37], 0, v[150:151]
	ds_read_b128 v[212:215], v169 offset:32768
	ds_read_b128 v[216:219], v169 offset:33792
	ds_read_b128 v[220:223], v169 offset:34816
	ds_read_b128 v[224:227], v169 offset:35840
	ds_read_b128 v[228:231], v169 offset:36864
	ds_read_b128 v[232:235], v169 offset:37888
	ds_read_b128 v[236:239], v169 offset:38912
	ds_read_b128 v[240:243], v169 offset:39936
	global_load_lds_dwordx4 v[250:251], off
	v_lshl_add_u64 v[250:251], s[36:37], 0, v[146:147]
	s_mov_b32 m0, s59
	s_nop 0
	global_load_lds_dwordx4 v[250:251], off
	s_waitcnt vmcnt(8)
	s_waitcnt lgkmcnt(0)
	s_barrier
	s_setprio 2
	v_mfma_f32_16x16x32_bf16 v[126:129], v[160:163], v[212:215], v[126:129]
	v_mfma_f32_16x16x32_bf16 v[122:125], v[170:173], v[212:215], v[122:125]
	v_mfma_f32_16x16x32_bf16 v[110:113], v[160:163], v[220:223], v[110:113]
	v_mfma_f32_16x16x32_bf16 v[106:109], v[170:173], v[220:223], v[106:109]
	v_mfma_f32_16x16x32_bf16 v[94:97], v[160:163], v[228:231], v[94:97]
	v_mfma_f32_16x16x32_bf16 v[90:93], v[170:173], v[228:231], v[90:93]
	v_mfma_f32_16x16x32_bf16 v[78:81], v[160:163], v[236:239], v[78:81]
	v_mfma_f32_16x16x32_bf16 v[74:77], v[170:173], v[236:239], v[74:77]
	s_setprio 0
	s_setprio 2
	v_mfma_f32_16x16x32_bf16 v[126:129], v[164:167], v[216:219], v[126:129]
	v_mfma_f32_16x16x32_bf16 v[122:125], v[174:177], v[216:219], v[122:125]
	v_mfma_f32_16x16x32_bf16 v[110:113], v[164:167], v[224:227], v[110:113]
	v_mfma_f32_16x16x32_bf16 v[106:109], v[174:177], v[224:227], v[106:109]
	v_mfma_f32_16x16x32_bf16 v[94:97], v[164:167], v[232:235], v[94:97]
	v_mfma_f32_16x16x32_bf16 v[90:93], v[174:177], v[232:235], v[90:93]
	v_mfma_f32_16x16x32_bf16 v[78:81], v[164:167], v[240:243], v[78:81]
	v_mfma_f32_16x16x32_bf16 v[74:77], v[174:177], v[240:243], v[74:77]
	s_setprio 0
	s_setprio 2
	v_mfma_f32_16x16x32_bf16 v[118:121], v[178:181], v[212:215], v[118:121]
	v_mfma_f32_16x16x32_bf16 v[114:117], v[204:207], v[212:215], v[114:117]
	v_mfma_f32_16x16x32_bf16 v[102:105], v[178:181], v[220:223], v[102:105]
	v_mfma_f32_16x16x32_bf16 v[98:101], v[204:207], v[220:223], v[98:101]
	v_mfma_f32_16x16x32_bf16 v[86:89], v[178:181], v[228:231], v[86:89]
	v_mfma_f32_16x16x32_bf16 v[82:85], v[204:207], v[228:231], v[82:85]
	v_mfma_f32_16x16x32_bf16 v[70:73], v[178:181], v[236:239], v[70:73]
	v_mfma_f32_16x16x32_bf16 v[66:69], v[204:207], v[236:239], v[66:69]
	s_setprio 0
	s_setprio 2
	v_mfma_f32_16x16x32_bf16 v[118:121], v[182:185], v[216:219], v[118:121]
	v_mfma_f32_16x16x32_bf16 v[114:117], v[208:211], v[216:219], v[114:117]
	v_mfma_f32_16x16x32_bf16 v[102:105], v[182:185], v[224:227], v[102:105]
	v_mfma_f32_16x16x32_bf16 v[98:101], v[208:211], v[224:227], v[98:101]
	v_mfma_f32_16x16x32_bf16 v[86:89], v[182:185], v[232:235], v[86:89]
	v_mfma_f32_16x16x32_bf16 v[82:85], v[208:211], v[232:235], v[82:85]
	v_mfma_f32_16x16x32_bf16 v[70:73], v[182:185], v[240:243], v[70:73]
	v_mfma_f32_16x16x32_bf16 v[66:69], v[208:211], v[240:243], v[66:69]
	s_setprio 1
	s_barrier
; #define PG8_STAGE(bufoff, gbase, voff) do { _Pragma("unroll") for (int _i = 0; _i < 2; ++_i) \
;         __builtin_amdgcn_global_load_lds((const unsigned*)((const char*)(gbase) + (voff)[_i]), (PG8_LAS unsigned*)(lds + (bufoff) + ldsw + _i * 8192), 16, 0, 0); } while (0)
; #define PG8_LDA(dst, b, h) do { _Pragma("unroll") for (int m = 0; m < 4; ++m) _Pragma("unroll") for (int k = 0; k < 2; ++k) dst[m][k] = *(const PG8_LAS bf16x8*)(lds + PG8_SA(b, h) + aoff + m * 2048 + k * 1024); } while (0)
; #define PG8_WAIT_V(n) asm volatile("s_waitcnt vmcnt(" #n ")" ::: "memory")
; template <class Epi, class Sched, bool ALIGN_EPI = false, bool SP2 = false>
; __device__ __forceinline__ void gemm_phase(PG8_LAS unsigned char* lds, const Gemm g, const Sched& S, const Epi& E) {
;     ...
;             PG8_LDA(At, 1, 1); PG8_STAGE(PG8_SB(1, 0), b3, voffB); PG8_STAGE(PG8_SB(1, 1), b3 + hstep, voffB); PG8_STAGE(PG8_SA(1, 0), a3, voffA);
;             PG8_WAIT_V(8); PG8_WAIT_L(0); PG8_BAR; PG8_MMA(1, 0, At, B0); PG8_MMA(1, 1, At, B1); PG8_BAR; PG8_SCHED;
;             } else {
;             PG8_LDB(B0, 0, 0); PG8_SCHED; PG8_LDA(At, 0, 0); PG8_STAGE(PG8_SA(1, 1), a1 + hstep, voffA);
;             PG8_WAIT_L(8); PG8_BAR; PG8_WAIT_L(0); PG8_MMA(0, 0, At, B0); PG8_BAR; PG8_SCHED;
;             PG8_LDB(B1, 0, 1); PG8_STAGE(PG8_SB(0, 0), b2, voffB);
;             PG8_BAR; PG8_WAIT_L(0); PG8_MMA(0, 1, At, B1); PG8_BAR;
;             PG8_LDA(At, 0, 1); PG8_STAGE(PG8_SA(0, 0), a2, voffA);
;             PG8_BAR; PG8_WAIT_L(0); PG8_MMA(1, 0, At, B0); PG8_BAR; PG8_SCHED;
;             PG8_STAGE(PG8_SB(0, 1), b2 + hstep, voffB);
;             PG8_WAIT_V(6); PG8_BAR; PG8_MMA(1, 1, At, B1); PG8_BAR;
;             PG8_LDB(B0, 1, 0); PG8_SCHED; PG8_LDA(At, 1, 0); PG8_STAGE(PG8_SA(0, 1), a2 + hstep, voffA);
;             PG8_WAIT_L(8); PG8_BAR; PG8_WAIT_L(0); PG8_MMA(0, 0, At, B0); PG8_BAR; PG8_SCHED;
;             PG8_LDB(B1, 1, 1); PG8_STAGE(PG8_SB(1, 0), b3, voffB);
;             PG8_BAR; PG8_WAIT_L(0); PG8_MMA(0, 1, At, B1); PG8_BAR;
;             PG8_LDA(At, 1, 1); PG8_STAGE(PG8_SA(1, 0), a3, voffA);
;             PG8_BAR; PG8_WAIT_L(0); PG8_MMA(1, 0, At, B0); PG8_BAR; PG8_SCHED;
;             PG8_STAGE(PG8_SB(1, 1), b3 + hstep, voffB);
;             PG8_WAIT_V(6); PG8_BAR; PG8_MMA(1, 1, At, B1); PG8_BAR;
;             }
;         }
;         if constexpr (ALIGN_EPI) { if (wr == 0) PG8_BAR; }
	s_add_i32 s36, s47, s4
	v_lshl_add_u64 v[186:187], v[186:187], 0, s[68:69]
	s_mov_b32 m0, s36
	ds_read_b128 v[212:215], v169 offset:49152
	ds_read_b128 v[216:219], v169 offset:50176
	ds_read_b128 v[220:223], v169 offset:51200
	ds_read_b128 v[224:227], v169 offset:52224
	ds_read_b128 v[228:231], v169 offset:53248
	ds_read_b128 v[232:235], v169 offset:54272
	ds_read_b128 v[236:239], v169 offset:55296
	ds_read_b128 v[240:243], v169 offset:56320
	global_load_lds_dwordx4 v[186:187], off
	s_add_i32 m0, s36, 0x2000
	s_add_u32 s18, s18, 0x60080
	v_lshl_add_u64 v[186:187], v[244:245], 0, s[68:69]
	s_addc_u32 s19, s19, 0
	s_add_i32 s36, s76, s4
	global_load_lds_dwordx4 v[186:187], off
	v_lshl_add_u64 v[186:187], s[18:19], 0, v[148:149]
	s_mov_b32 m0, s36
	s_nop 0
	global_load_lds_dwordx4 v[186:187], off
	v_lshl_add_u64 v[186:187], s[18:19], 0, v[144:145]
	s_add_i32 m0, s36, 0x2000
	s_nop 0
	global_load_lds_dwordx4 v[186:187], off
	v_lshl_add_u64 v[186:187], v[246:247], 0, s[68:69]
	s_mov_b32 m0, s62
	s_nop 0
	global_load_lds_dwordx4 v[186:187], off
	v_lshl_add_u64 v[186:187], v[248:249], 0, s[68:69]
	s_mov_b32 m0, s63
	s_nop 0
	global_load_lds_dwordx4 v[186:187], off
	s_nop 0
	s_waitcnt vmcnt(8)
	s_waitcnt lgkmcnt(0)
	s_barrier
	s_setprio 2
	v_mfma_f32_16x16x32_bf16 v[62:65], v[160:163], v[212:215], v[62:65]
	v_mfma_f32_16x16x32_bf16 v[58:61], v[170:173], v[212:215], v[58:61]
	v_mfma_f32_16x16x32_bf16 v[46:49], v[160:163], v[220:223], v[46:49]
	v_mfma_f32_16x16x32_bf16 v[42:45], v[170:173], v[220:223], v[42:45]
	v_mfma_f32_16x16x32_bf16 v[30:33], v[160:163], v[228:231], v[30:33]
	v_mfma_f32_16x16x32_bf16 v[26:29], v[170:173], v[228:231], v[26:29]
	v_mfma_f32_16x16x32_bf16 v[14:17], v[160:163], v[236:239], v[14:17]
	v_mfma_f32_16x16x32_bf16 v[10:13], v[170:173], v[236:239], v[10:13]
	s_setprio 0
	s_setprio 2
	v_mfma_f32_16x16x32_bf16 v[62:65], v[164:167], v[216:219], v[62:65]
	v_mfma_f32_16x16x32_bf16 v[58:61], v[174:177], v[216:219], v[58:61]
	v_mfma_f32_16x16x32_bf16 v[46:49], v[164:167], v[224:227], v[46:49]
	v_mfma_f32_16x16x32_bf16 v[42:45], v[174:177], v[224:227], v[42:45]
	v_mfma_f32_16x16x32_bf16 v[30:33], v[164:167], v[232:235], v[30:33]
	v_mfma_f32_16x16x32_bf16 v[26:29], v[174:177], v[232:235], v[26:29]
	v_mfma_f32_16x16x32_bf16 v[14:17], v[164:167], v[240:243], v[14:17]
	v_mfma_f32_16x16x32_bf16 v[10:13], v[174:177], v[240:243], v[10:13]
	s_setprio 0
	s_setprio 2
	v_mfma_f32_16x16x32_bf16 v[54:57], v[178:181], v[212:215], v[54:57]
	v_mfma_f32_16x16x32_bf16 v[50:53], v[204:207], v[212:215], v[50:53]
	v_mfma_f32_16x16x32_bf16 v[38:41], v[178:181], v[220:223], v[38:41]
	v_mfma_f32_16x16x32_bf16 v[34:37], v[204:207], v[220:223], v[34:37]
	v_mfma_f32_16x16x32_bf16 v[22:25], v[178:181], v[228:231], v[22:25]
	v_mfma_f32_16x16x32_bf16 v[18:21], v[204:207], v[228:231], v[18:21]
	v_mfma_f32_16x16x32_bf16 v[6:9], v[178:181], v[236:239], v[6:9]
	v_mfma_f32_16x16x32_bf16 v[2:5], v[204:207], v[236:239], v[2:5]
	s_setprio 0
	s_setprio 2
	v_mfma_f32_16x16x32_bf16 v[54:57], v[182:185], v[216:219], v[54:57]
	v_mfma_f32_16x16x32_bf16 v[50:53], v[208:211], v[216:219], v[50:53]
	v_mfma_f32_16x16x32_bf16 v[38:41], v[182:185], v[224:227], v[38:41]
	v_mfma_f32_16x16x32_bf16 v[34:37], v[208:211], v[224:227], v[34:37]
	v_mfma_f32_16x16x32_bf16 v[22:25], v[182:185], v[232:235], v[22:25]
	v_mfma_f32_16x16x32_bf16 v[18:21], v[208:211], v[232:235], v[18:21]
	v_mfma_f32_16x16x32_bf16 v[6:9], v[182:185], v[240:243], v[6:9]
	v_mfma_f32_16x16x32_bf16 v[2:5], v[208:211], v[240:243], v[2:5]
	s_setprio 1
	s_barrier
	s_add_i32 s46, s46, 2
	s_add_u32 s60, s60, 0x100
	s_addc_u32 s73, s73, 0
	s_cmp_gt_u32 s46, 21
	s_mov_b64 s[36:37], s[42:43]
	s_cbranch_scc0 .LBB0_160
	s_and_b64 vcc, exec, s[10:11]
	s_cbranch_vccz .LBB0_163
	s_barrier

; #define PG8_STAGE(bufoff, gbase, voff) do { _Pragma("unroll") for (int _i = 0; _i < 2; ++_i) \
;         __builtin_amdgcn_global_load_lds((const unsigned*)((const char*)(gbase) + (voff)[_i]), (PG8_LAS unsigned*)(lds + (bufoff) + ldsw + _i * 8192), 16, 0, 0); } while (0)
; #define PG8_LDA(dst, b, h) do { _Pragma("unroll") for (int m = 0; m < 4; ++m) _Pragma("unroll") for (int k = 0; k < 2; ++k) dst[m][k] = *(const PG8_LAS bf16x8*)(lds + PG8_SA(b, h) + aoff + m * 2048 + k * 1024); } while (0)
; #define PG8_LDB(dst, b, h) do { _Pragma("unroll") for (int n = 0; n < 2; ++n) _Pragma("unroll") for (int k = 0; k < 2; ++k) dst[n][k] = *(const PG8_LAS bf16x8*)(lds + PG8_SB(b, h) + boff + n * 2048 + k * 1024); } while (0)
; #define PG8_MMA(ai, bj, At, Bt) do { __builtin_amdgcn_s_setprio(1); _Pragma("unroll") for (int m = 0; m < 4; ++m) _Pragma("unroll") for (int n = 0; n < 2; ++n) _Pragma("unroll") for (int k = 0; k < 2; ++k) \
;         acc[ai][bj][m][n] = __builtin_amdgcn_mfma_f32_16x16x32_bf16(Bt[n][k], At[m][k], acc[ai][bj][m][n], 0, 0, 0); __builtin_amdgcn_s_setprio(0); } while (0)
; #define PG8_WAIT_V(n) asm volatile("s_waitcnt vmcnt(" #n ")" ::: "memory")
; #define PG8_BAR __builtin_amdgcn_s_barrier()
; template <class Epi, class Sched, bool ALIGN_EPI = false, bool SP2 = false>
; __device__ __forceinline__ void gemm_phase(PG8_LAS unsigned char* lds, const Gemm g, const Sched& S, const Epi& E) {
;     ...
;         for (int t = 0; t < nt; t += 2) {
;             const bool last = (t == nt - 2);
;             const char* a1 = cA + (size_t)(t + 1) * kstep;
;             const char* a2 = last ? nA : cA + (size_t)(t + 2) * kstep; const char* b2 = last ? nB : cB + (size_t)(t + 2) * kstep;
;             const char* a3 = a2 + kstep; const char* b3 = b2 + kstep;
;             if (last && has_next) S.a_ready(nxt);
;             if constexpr (SP2) {
;             PG8_LDB(B0, 0, 0); PG8_LDB(B1, 0, 1); PG8_SCHED; PG8_LDA(At, 0, 0); PG8_STAGE(PG8_SA(1, 1), a1 + hstep, voffA);
;             PG8_WAIT_V(8); PG8_WAIT_L(0); PG8_BAR; PG8_MMA(0, 0, At, B0); PG8_MMA(0, 1, At, B1); PG8_BAR; PG8_SCHED;
;             PG8_LDA(At, 0, 1); PG8_STAGE(PG8_SB(0, 0), b2, voffB); PG8_STAGE(PG8_SB(0, 1), b2 + hstep, voffB); PG8_STAGE(PG8_SA(0, 0), a2, voffA);
;             PG8_WAIT_V(8); PG8_WAIT_L(0); PG8_BAR; PG8_MMA(1, 0, At, B0); PG8_MMA(1, 1, At, B1); PG8_BAR; PG8_SCHED;
.LBB0_281:
	s_add_u32 s18, s36, 0xfff80080
	s_addc_u32 s19, s37, -1
	s_add_i32 s73, 0, 0x10000
	s_cmp_eq_u32 s67, 28
	s_cselect_b32 s43, s9, s19
	s_cselect_b32 s42, s59, s18
	v_add_u32_e32 v163, s73, v160
	s_cselect_b32 s19, s7, s63
	s_cselect_b32 s18, s60, s62
	s_add_i32 s76, 0, 0x14000
	ds_read_b128 v[156:159], v163
	ds_read_b128 v[164:167], v163 offset:1024
	ds_read_b128 v[168:171], v163 offset:2048
	ds_read_b128 v[172:175], v163 offset:3072
	v_add_u32_e32 v163, s76, v160
	ds_read_b128 v[176:179], v163
	ds_read_b128 v[180:183], v163 offset:1024
	ds_read_b128 v[184:187], v163 offset:2048
	ds_read_b128 v[204:207], v163 offset:3072
	v_lshl_add_u64 v[240:241], s[36:37], 0, v[152:153]
	s_add_i32 m0, s30, 0xc000
	ds_read_b128 v[208:211], v162
	ds_read_b128 v[212:215], v162 offset:1024
	ds_read_b128 v[216:219], v162 offset:2048
	ds_read_b128 v[220:223], v162 offset:3072
	ds_read_b128 v[224:227], v162 offset:4096
	ds_read_b128 v[228:231], v162 offset:5120
	ds_read_b128 v[232:235], v162 offset:6144
	ds_read_b128 v[236:239], v162 offset:7168
	global_load_lds_dwordx4 v[240:241], off
	v_lshl_add_u64 v[240:241], s[36:37], 0, v[154:155]
	s_add_i32 m0, s30, 0xe000
	s_nop 0
	global_load_lds_dwordx4 v[240:241], off
	s_nop 0
	s_nop 0
	s_waitcnt vmcnt(8)
	s_waitcnt lgkmcnt(0)
	s_barrier
	s_setprio 2
	v_mfma_f32_16x16x32_bf16 v[126:129], v[156:159], v[208:211], v[126:129]
	v_mfma_f32_16x16x32_bf16 v[122:125], v[168:171], v[208:211], v[122:125]
	v_mfma_f32_16x16x32_bf16 v[110:113], v[156:159], v[216:219], v[110:113]
	v_mfma_f32_16x16x32_bf16 v[106:109], v[168:171], v[216:219], v[106:109]
	v_mfma_f32_16x16x32_bf16 v[94:97], v[156:159], v[224:227], v[94:97]
	v_mfma_f32_16x16x32_bf16 v[90:93], v[168:171], v[224:227], v[90:93]
	v_mfma_f32_16x16x32_bf16 v[78:81], v[156:159], v[232:235], v[78:81]
	v_mfma_f32_16x16x32_bf16 v[74:77], v[168:171], v[232:235], v[74:77]
	s_setprio 0
	s_setprio 2
	v_mfma_f32_16x16x32_bf16 v[126:129], v[164:167], v[212:215], v[126:129]
	v_mfma_f32_16x16x32_bf16 v[122:125], v[172:175], v[212:215], v[122:125]
	v_mfma_f32_16x16x32_bf16 v[110:113], v[164:167], v[220:223], v[110:113]
	v_mfma_f32_16x16x32_bf16 v[106:109], v[172:175], v[220:223], v[106:109]
	v_mfma_f32_16x16x32_bf16 v[94:97], v[164:167], v[228:231], v[94:97]
	v_mfma_f32_16x16x32_bf16 v[90:93], v[172:175], v[228:231], v[90:93]
	v_mfma_f32_16x16x32_bf16 v[78:81], v[164:167], v[236:239], v[78:81]
	v_mfma_f32_16x16x32_bf16 v[74:77], v[172:175], v[236:239], v[74:77]
	s_setprio 0
	s_setprio 2
	v_mfma_f32_16x16x32_bf16 v[118:121], v[176:179], v[208:211], v[118:121]
	v_mfma_f32_16x16x32_bf16 v[114:117], v[184:187], v[208:211], v[114:117]
	v_mfma_f32_16x16x32_bf16 v[102:105], v[176:179], v[216:219], v[102:105]
	v_mfma_f32_16x16x32_bf16 v[98:101], v[184:187], v[216:219], v[98:101]
	v_mfma_f32_16x16x32_bf16 v[86:89], v[176:179], v[224:227], v[86:89]
	v_mfma_f32_16x16x32_bf16 v[82:85], v[184:187], v[224:227], v[82:85]
	v_mfma_f32_16x16x32_bf16 v[70:73], v[176:179], v[232:235], v[70:73]
	v_mfma_f32_16x16x32_bf16 v[66:69], v[184:187], v[232:235], v[66:69]
	s_setprio 0
	s_setprio 2
	v_mfma_f32_16x16x32_bf16 v[118:121], v[180:183], v[212:215], v[118:121]
	v_mfma_f32_16x16x32_bf16 v[114:117], v[204:207], v[212:215], v[114:117]
	v_mfma_f32_16x16x32_bf16 v[102:105], v[180:183], v[220:223], v[102:105]
	v_mfma_f32_16x16x32_bf16 v[98:101], v[204:207], v[220:223], v[98:101]
	v_mfma_f32_16x16x32_bf16 v[86:89], v[180:183], v[228:231], v[86:89]
	v_mfma_f32_16x16x32_bf16 v[82:85], v[204:207], v[228:231], v[82:85]
	v_mfma_f32_16x16x32_bf16 v[70:73], v[180:183], v[236:239], v[70:73]
	v_mfma_f32_16x16x32_bf16 v[66:69], v[204:207], v[236:239], v[66:69]
	s_setprio 1
	s_barrier
	s_add_i32 s73, s73, s28
	v_lshl_add_u64 v[240:241], s[18:19], 0, v[146:147]
	s_mov_b32 m0, s73
	ds_read_b128 v[208:211], v162 offset:16384
	ds_read_b128 v[212:215], v162 offset:17408
	ds_read_b128 v[216:219], v162 offset:18432
	ds_read_b128 v[220:223], v162 offset:19456
	ds_read_b128 v[224:227], v162 offset:20480
	ds_read_b128 v[228:231], v162 offset:21504
	ds_read_b128 v[232:235], v162 offset:22528
	ds_read_b128 v[236:239], v162 offset:23552
	global_load_lds_dwordx4 v[240:241], off
	s_add_i32 m0, s73, 0x2000
	s_add_u32 s78, s18, 0x80000
	v_lshl_add_u64 v[242:243], s[18:19], 0, v[142:143]
	s_addc_u32 s79, s19, 0
	s_add_i32 s73, s76, s28
	global_load_lds_dwordx4 v[242:243], off
	v_lshl_add_u64 v[244:245], s[78:79], 0, v[146:147]
	s_mov_b32 m0, s73
	v_lshl_add_u64 v[246:247], s[42:43], 0, v[144:145]
	global_load_lds_dwordx4 v[244:245], off
	v_lshl_add_u64 v[244:245], s[78:79], 0, v[142:143]
	s_add_i32 m0, s73, 0x2000
	s_nop 0
	global_load_lds_dwordx4 v[244:245], off
	v_lshl_add_u64 v[244:245], s[42:43], 0, v[148:149]
	s_mov_b32 m0, s30
	s_nop 0
	global_load_lds_dwordx4 v[244:245], off
	s_mov_b32 m0, s34
	s_nop 0
	global_load_lds_dwordx4 v[246:247], off
	s_waitcnt vmcnt(8)
	s_waitcnt lgkmcnt(0)
	s_barrier
; #define PG8_STAGE(bufoff, gbase, voff) do { _Pragma("unroll") for (int _i = 0; _i < 2; ++_i) \
;         __builtin_amdgcn_global_load_lds((const unsigned*)((const char*)(gbase) + (voff)[_i]), (PG8_LAS unsigned*)(lds + (bufoff) + ldsw + _i * 8192), 16, 0, 0); } while (0)
; #define PG8_LDA(dst, b, h) do { _Pragma("unroll") for (int m = 0; m < 4; ++m) _Pragma("unroll") for (int k = 0; k < 2; ++k) dst[m][k] = *(const PG8_LAS bf16x8*)(lds + PG8_SA(b, h) + aoff + m * 2048 + k * 1024); } while (0)
; #define PG8_LDB(dst, b, h) do { _Pragma("unroll") for (int n = 0; n < 2; ++n) _Pragma("unroll") for (int k = 0; k < 2; ++k) dst[n][k] = *(const PG8_LAS bf16x8*)(lds + PG8_SB(b, h) + boff + n * 2048 + k * 1024); } while (0)
; #define PG8_MMA(ai, bj, At, Bt) do { __builtin_amdgcn_s_setprio(1); _Pragma("unroll") for (int m = 0; m < 4; ++m) _Pragma("unroll") for (int n = 0; n < 2; ++n) _Pragma("unroll") for (int k = 0; k < 2; ++k) \
;         acc[ai][bj][m][n] = __builtin_amdgcn_mfma_f32_16x16x32_bf16(Bt[n][k], At[m][k], acc[ai][bj][m][n], 0, 0, 0); __builtin_amdgcn_s_setprio(0); } while (0)
; #define PG8_WAIT_V(n) asm volatile("s_waitcnt vmcnt(" #n ")" ::: "memory")
; #define PG8_WAIT_L(n) asm volatile("s_waitcnt lgkmcnt(" #n ")" ::: "memory")
; #define PG8_BAR __builtin_amdgcn_s_barrier()
; #define PG8_SCHED __builtin_amdgcn_sched_barrier(0)
; template <class Epi, class Sched, bool ALIGN_EPI = false, bool SP2 = false>
; __device__ __forceinline__ void gemm_phase(PG8_LAS unsigned char* lds, const Gemm g, const Sched& S, const Epi& E) {
;     ...
;             PG8_WAIT_V(8); PG8_WAIT_L(0); PG8_BAR; PG8_MMA(1, 0, At, B0); PG8_MMA(1, 1, At, B1); PG8_BAR; PG8_SCHED;
;             PG8_LDB(B0, 1, 0); PG8_LDB(B1, 1, 1); PG8_SCHED; PG8_LDA(At, 1, 0); PG8_STAGE(PG8_SA(0, 1), a2 + hstep, voffA);
;             PG8_WAIT_V(8); PG8_WAIT_L(0); PG8_BAR; PG8_MMA(0, 0, At, B0); PG8_MMA(0, 1, At, B1); PG8_BAR; PG8_SCHED;
	s_setprio 2
	v_mfma_f32_16x16x32_bf16 v[62:65], v[156:159], v[208:211], v[62:65]
	v_mfma_f32_16x16x32_bf16 v[58:61], v[168:171], v[208:211], v[58:61]
	v_mfma_f32_16x16x32_bf16 v[46:49], v[156:159], v[216:219], v[46:49]
	v_mfma_f32_16x16x32_bf16 v[42:45], v[168:171], v[216:219], v[42:45]
	v_mfma_f32_16x16x32_bf16 v[30:33], v[156:159], v[224:227], v[30:33]
	v_mfma_f32_16x16x32_bf16 v[26:29], v[168:171], v[224:227], v[26:29]
	v_mfma_f32_16x16x32_bf16 v[14:17], v[156:159], v[232:235], v[14:17]
	v_mfma_f32_16x16x32_bf16 v[10:13], v[168:171], v[232:235], v[10:13]
	s_setprio 0
	s_setprio 2
	v_mfma_f32_16x16x32_bf16 v[62:65], v[164:167], v[212:215], v[62:65]
	v_mfma_f32_16x16x32_bf16 v[58:61], v[172:175], v[212:215], v[58:61]
	v_mfma_f32_16x16x32_bf16 v[46:49], v[164:167], v[220:223], v[46:49]
	v_mfma_f32_16x16x32_bf16 v[42:45], v[172:175], v[220:223], v[42:45]
	v_mfma_f32_16x16x32_bf16 v[30:33], v[164:167], v[228:231], v[30:33]
	v_mfma_f32_16x16x32_bf16 v[26:29], v[172:175], v[228:231], v[26:29]
	v_mfma_f32_16x16x32_bf16 v[14:17], v[164:167], v[236:239], v[14:17]
	v_mfma_f32_16x16x32_bf16 v[10:13], v[172:175], v[236:239], v[10:13]
	s_setprio 0
	s_setprio 2
	v_mfma_f32_16x16x32_bf16 v[54:57], v[176:179], v[208:211], v[54:57]
	v_mfma_f32_16x16x32_bf16 v[50:53], v[184:187], v[208:211], v[50:53]
	v_mfma_f32_16x16x32_bf16 v[38:41], v[176:179], v[216:219], v[38:41]
	v_mfma_f32_16x16x32_bf16 v[34:37], v[184:187], v[216:219], v[34:37]
	v_mfma_f32_16x16x32_bf16 v[22:25], v[176:179], v[224:227], v[22:25]
	v_mfma_f32_16x16x32_bf16 v[18:21], v[184:187], v[224:227], v[18:21]
	v_mfma_f32_16x16x32_bf16 v[6:9], v[176:179], v[232:235], v[6:9]
	v_mfma_f32_16x16x32_bf16 v[2:5], v[184:187], v[232:235], v[2:5]
	s_setprio 0
	s_setprio 2
	v_mfma_f32_16x16x32_bf16 v[54:57], v[180:183], v[212:215], v[54:57]
	v_mfma_f32_16x16x32_bf16 v[50:53], v[204:207], v[212:215], v[50:53]
	v_mfma_f32_16x16x32_bf16 v[38:41], v[180:183], v[220:223], v[38:41]
	v_mfma_f32_16x16x32_bf16 v[34:37], v[204:207], v[220:223], v[34:37]
	v_mfma_f32_16x16x32_bf16 v[22:25], v[180:183], v[228:231], v[22:25]
	v_mfma_f32_16x16x32_bf16 v[18:21], v[204:207], v[228:231], v[18:21]
	v_mfma_f32_16x16x32_bf16 v[6:9], v[180:183], v[236:239], v[6:9]
	v_mfma_f32_16x16x32_bf16 v[2:5], v[204:207], v[236:239], v[2:5]
	s_setprio 1
	s_barrier
	s_add_i32 s73, 0, 0x18000
	v_add_u32_e32 v163, s73, v160
	s_add_i32 s76, 0, 0x1c000
	ds_read_b128 v[156:159], v163
	ds_read_b128 v[164:167], v163 offset:1024
	ds_read_b128 v[168:171], v163 offset:2048
	ds_read_b128 v[172:175], v163 offset:3072
	v_add_u32_e32 v163, s76, v160
	ds_read_b128 v[176:179], v163
	ds_read_b128 v[180:183], v163 offset:1024
	ds_read_b128 v[184:187], v163 offset:2048
	ds_read_b128 v[204:207], v163 offset:3072
	s_add_u32 s42, s42, 0x80000
	s_addc_u32 s43, s43, 0
	s_mov_b32 m0, s44
	v_lshl_add_u64 v[248:249], s[42:43], 0, v[148:149]
	ds_read_b128 v[208:211], v162 offset:32768
	ds_read_b128 v[212:215], v162 offset:33792
	ds_read_b128 v[216:219], v162 offset:34816
	ds_read_b128 v[220:223], v162 offset:35840
	ds_read_b128 v[224:227], v162 offset:36864
	ds_read_b128 v[228:231], v162 offset:37888
	ds_read_b128 v[232:235], v162 offset:38912
	ds_read_b128 v[236:239], v162 offset:39936
	global_load_lds_dwordx4 v[248:249], off
	v_lshl_add_u64 v[248:249], s[42:43], 0, v[144:145]
	s_mov_b32 m0, s45
	s_nop 0
	global_load_lds_dwordx4 v[248:249], off
	s_waitcnt vmcnt(8)
	s_waitcnt lgkmcnt(0)
	s_barrier
	s_setprio 2
	v_mfma_f32_16x16x32_bf16 v[126:129], v[156:159], v[208:211], v[126:129]
	v_mfma_f32_16x16x32_bf16 v[122:125], v[168:171], v[208:211], v[122:125]
	v_mfma_f32_16x16x32_bf16 v[110:113], v[156:159], v[216:219], v[110:113]
	v_mfma_f32_16x16x32_bf16 v[106:109], v[168:171], v[216:219], v[106:109]
	v_mfma_f32_16x16x32_bf16 v[94:97], v[156:159], v[224:227], v[94:97]
	v_mfma_f32_16x16x32_bf16 v[90:93], v[168:171], v[224:227], v[90:93]
	v_mfma_f32_16x16x32_bf16 v[78:81], v[156:159], v[232:235], v[78:81]
	v_mfma_f32_16x16x32_bf16 v[74:77], v[168:171], v[232:235], v[74:77]
	s_setprio 0
	s_setprio 2
	v_mfma_f32_16x16x32_bf16 v[126:129], v[164:167], v[212:215], v[126:129]
	v_mfma_f32_16x16x32_bf16 v[122:125], v[172:175], v[212:215], v[122:125]
	v_mfma_f32_16x16x32_bf16 v[110:113], v[164:167], v[220:223], v[110:113]
	v_mfma_f32_16x16x32_bf16 v[106:109], v[172:175], v[220:223], v[106:109]
	v_mfma_f32_16x16x32_bf16 v[94:97], v[164:167], v[228:231], v[94:97]
	v_mfma_f32_16x16x32_bf16 v[90:93], v[172:175], v[228:231], v[90:93]
	v_mfma_f32_16x16x32_bf16 v[78:81], v[164:167], v[236:239], v[78:81]
	v_mfma_f32_16x16x32_bf16 v[74:77], v[172:175], v[236:239], v[74:77]
	s_setprio 0
	s_setprio 2
	v_mfma_f32_16x16x32_bf16 v[118:121], v[176:179], v[208:211], v[118:121]
	v_mfma_f32_16x16x32_bf16 v[114:117], v[184:187], v[208:211], v[114:117]
	v_mfma_f32_16x16x32_bf16 v[102:105], v[176:179], v[216:219], v[102:105]
	v_mfma_f32_16x16x32_bf16 v[98:101], v[184:187], v[216:219], v[98:101]
	v_mfma_f32_16x16x32_bf16 v[86:89], v[176:179], v[224:227], v[86:89]
	v_mfma_f32_16x16x32_bf16 v[82:85], v[184:187], v[224:227], v[82:85]
	v_mfma_f32_16x16x32_bf16 v[70:73], v[176:179], v[232:235], v[70:73]
	v_mfma_f32_16x16x32_bf16 v[66:69], v[184:187], v[232:235], v[66:69]
	s_setprio 0
	s_setprio 2
	v_mfma_f32_16x16x32_bf16 v[118:121], v[180:183], v[212:215], v[118:121]
	v_mfma_f32_16x16x32_bf16 v[114:117], v[204:207], v[212:215], v[114:117]
	v_mfma_f32_16x16x32_bf16 v[102:105], v[180:183], v[220:223], v[102:105]
	v_mfma_f32_16x16x32_bf16 v[98:101], v[204:207], v[220:223], v[98:101]
	v_mfma_f32_16x16x32_bf16 v[86:89], v[180:183], v[228:231], v[86:89]
	v_mfma_f32_16x16x32_bf16 v[82:85], v[204:207], v[228:231], v[82:85]
	v_mfma_f32_16x16x32_bf16 v[70:73], v[180:183], v[236:239], v[70:73]
	v_mfma_f32_16x16x32_bf16 v[66:69], v[204:207], v[236:239], v[66:69]
	s_setprio 1
	s_barrier
; #define PG8_STAGE(bufoff, gbase, voff) do { _Pragma("unroll") for (int _i = 0; _i < 2; ++_i) \
;         __builtin_amdgcn_global_load_lds((const unsigned*)((const char*)(gbase) + (voff)[_i]), (PG8_LAS unsigned*)(lds + (bufoff) + ldsw + _i * 8192), 16, 0, 0); } while (0)
; #define PG8_BAR __builtin_amdgcn_s_barrier()
;     __device__ __forceinline__ void operator()(const f32x4 (&acc)[2][2][4][2], const Unit& u, int wr, int wc, int fr, int fq) const {
;         const int row0 = u.pm * BM + wr * 64 + fr, col0 = u.pn * BM + wc * 32 + 8 * fq;
;         if (u.pn >= 30) {
; template <class Epi, class Sched, bool ALIGN_EPI = false, bool SP2 = false>
; __device__ __forceinline__ void gemm_phase(PG8_LAS unsigned char* lds, const Gemm g, const Sched& S, const Epi& E) {
;     ...
;             PG8_LDA(At, 1, 1); PG8_STAGE(PG8_SB(1, 0), b3, voffB); PG8_STAGE(PG8_SB(1, 1), b3 + hstep, voffB); PG8_STAGE(PG8_SA(1, 0), a3, voffA);
;             PG8_WAIT_V(8); PG8_WAIT_L(0); PG8_BAR; PG8_MMA(1, 0, At, B0); PG8_MMA(1, 1, At, B1); PG8_BAR; PG8_SCHED;
;             } else {
;             PG8_LDB(B0, 0, 0); PG8_SCHED; PG8_LDA(At, 0, 0); PG8_STAGE(PG8_SA(1, 1), a1 + hstep, voffA);
;             PG8_WAIT_L(8); PG8_BAR; PG8_WAIT_L(0); PG8_MMA(0, 0, At, B0); PG8_BAR; PG8_SCHED;
;             PG8_LDB(B1, 0, 1); PG8_STAGE(PG8_SB(0, 0), b2, voffB);
;             PG8_BAR; PG8_WAIT_L(0); PG8_MMA(0, 1, At, B1); PG8_BAR;
;             PG8_LDA(At, 0, 1); PG8_STAGE(PG8_SA(0, 0), a2, voffA);
;             PG8_BAR; PG8_WAIT_L(0); PG8_MMA(1, 0, At, B0); PG8_BAR; PG8_SCHED;
;             PG8_STAGE(PG8_SB(0, 1), b2 + hstep, voffB);
;             PG8_WAIT_V(6); PG8_BAR; PG8_MMA(1, 1, At, B1); PG8_BAR;
;             PG8_LDB(B0, 1, 0); PG8_SCHED; PG8_LDA(At, 1, 0); PG8_STAGE(PG8_SA(0, 1), a2 + hstep, voffA);
;             PG8_WAIT_L(8); PG8_BAR; PG8_WAIT_L(0); PG8_MMA(0, 0, At, B0); PG8_BAR; PG8_SCHED;
;             PG8_LDB(B1, 1, 1); PG8_STAGE(PG8_SB(1, 0), b3, voffB);
;             PG8_BAR; PG8_WAIT_L(0); PG8_MMA(0, 1, At, B1); PG8_BAR;
;             PG8_LDA(At, 1, 1); PG8_STAGE(PG8_SA(1, 0), a3, voffA);
;             PG8_BAR; PG8_WAIT_L(0); PG8_MMA(1, 0, At, B0); PG8_BAR; PG8_SCHED;
;             PG8_STAGE(PG8_SB(1, 1), b3 + hstep, voffB);
;             PG8_WAIT_V(6); PG8_BAR; PG8_MMA(1, 1, At, B1); PG8_BAR;
;             }
;         }
;         if constexpr (ALIGN_EPI) { if (wr == 0) PG8_BAR; }
	s_add_i32 s42, s73, s28
	v_lshl_add_u64 v[240:241], v[240:241], 0, s[68:69]
	s_mov_b32 m0, s42
	ds_read_b128 v[208:211], v162 offset:49152
	ds_read_b128 v[212:215], v162 offset:50176
	ds_read_b128 v[216:219], v162 offset:51200
	ds_read_b128 v[220:223], v162 offset:52224
	ds_read_b128 v[224:227], v162 offset:53248
	ds_read_b128 v[228:231], v162 offset:54272
	ds_read_b128 v[232:235], v162 offset:55296
	ds_read_b128 v[236:239], v162 offset:56320
	global_load_lds_dwordx4 v[240:241], off
	s_add_i32 m0, s42, 0x2000
	s_add_u32 s18, s18, 0x80080
	v_lshl_add_u64 v[240:241], v[242:243], 0, s[68:69]
	s_addc_u32 s19, s19, 0
	s_add_i32 s42, s76, s28
	global_load_lds_dwordx4 v[240:241], off
	v_lshl_add_u64 v[240:241], s[18:19], 0, v[146:147]
	s_mov_b32 m0, s42
	s_nop 0
	global_load_lds_dwordx4 v[240:241], off
	v_lshl_add_u64 v[240:241], s[18:19], 0, v[142:143]
	s_add_i32 m0, s42, 0x2000
	s_nop 0
	global_load_lds_dwordx4 v[240:241], off
	v_lshl_add_u64 v[240:241], v[244:245], 0, s[68:69]
	s_mov_b32 m0, s46
	s_nop 0
	global_load_lds_dwordx4 v[240:241], off
	v_lshl_add_u64 v[240:241], v[246:247], 0, s[68:69]
	s_mov_b32 m0, s47
	s_nop 0
	global_load_lds_dwordx4 v[240:241], off
	s_nop 0
	s_waitcnt vmcnt(8)
	s_waitcnt lgkmcnt(0)
	s_barrier
	s_setprio 2
	v_mfma_f32_16x16x32_bf16 v[62:65], v[156:159], v[208:211], v[62:65]
	v_mfma_f32_16x16x32_bf16 v[58:61], v[168:171], v[208:211], v[58:61]
	v_mfma_f32_16x16x32_bf16 v[46:49], v[156:159], v[216:219], v[46:49]
	v_mfma_f32_16x16x32_bf16 v[42:45], v[168:171], v[216:219], v[42:45]
	v_mfma_f32_16x16x32_bf16 v[30:33], v[156:159], v[224:227], v[30:33]
	v_mfma_f32_16x16x32_bf16 v[26:29], v[168:171], v[224:227], v[26:29]
	v_mfma_f32_16x16x32_bf16 v[14:17], v[156:159], v[232:235], v[14:17]
	v_mfma_f32_16x16x32_bf16 v[10:13], v[168:171], v[232:235], v[10:13]
	s_setprio 0
	s_setprio 2
	v_mfma_f32_16x16x32_bf16 v[62:65], v[164:167], v[212:215], v[62:65]
	v_mfma_f32_16x16x32_bf16 v[58:61], v[172:175], v[212:215], v[58:61]
	v_mfma_f32_16x16x32_bf16 v[46:49], v[164:167], v[220:223], v[46:49]
	v_mfma_f32_16x16x32_bf16 v[42:45], v[172:175], v[220:223], v[42:45]
	v_mfma_f32_16x16x32_bf16 v[30:33], v[164:167], v[228:231], v[30:33]
	v_mfma_f32_16x16x32_bf16 v[26:29], v[172:175], v[228:231], v[26:29]
	v_mfma_f32_16x16x32_bf16 v[14:17], v[164:167], v[236:239], v[14:17]
	v_mfma_f32_16x16x32_bf16 v[10:13], v[172:175], v[236:239], v[10:13]
	s_setprio 0
	s_setprio 2
	v_mfma_f32_16x16x32_bf16 v[54:57], v[176:179], v[208:211], v[54:57]
	v_mfma_f32_16x16x32_bf16 v[50:53], v[184:187], v[208:211], v[50:53]
	v_mfma_f32_16x16x32_bf16 v[38:41], v[176:179], v[216:219], v[38:41]
	v_mfma_f32_16x16x32_bf16 v[34:37], v[184:187], v[216:219], v[34:37]
	v_mfma_f32_16x16x32_bf16 v[22:25], v[176:179], v[224:227], v[22:25]
	v_mfma_f32_16x16x32_bf16 v[18:21], v[184:187], v[224:227], v[18:21]
	v_mfma_f32_16x16x32_bf16 v[6:9], v[176:179], v[232:235], v[6:9]
	v_mfma_f32_16x16x32_bf16 v[2:5], v[184:187], v[232:235], v[2:5]
	s_setprio 0
	s_setprio 2
	v_mfma_f32_16x16x32_bf16 v[54:57], v[180:183], v[212:215], v[54:57]
	v_mfma_f32_16x16x32_bf16 v[50:53], v[204:207], v[212:215], v[50:53]
	v_mfma_f32_16x16x32_bf16 v[38:41], v[180:183], v[220:223], v[38:41]
	v_mfma_f32_16x16x32_bf16 v[34:37], v[204:207], v[220:223], v[34:37]
	v_mfma_f32_16x16x32_bf16 v[22:25], v[180:183], v[228:231], v[22:25]
	v_mfma_f32_16x16x32_bf16 v[18:21], v[204:207], v[228:231], v[18:21]
	v_mfma_f32_16x16x32_bf16 v[6:9], v[180:183], v[236:239], v[6:9]
	v_mfma_f32_16x16x32_bf16 v[2:5], v[204:207], v[236:239], v[2:5]
	s_setprio 1
	s_barrier
	s_add_i32 s67, s67, 2
	s_add_u32 s36, s36, 0x100
	s_addc_u32 s37, s37, 0
	s_add_u32 s62, s62, 0x100
	s_addc_u32 s63, s63, 0
	s_cmp_gt_u32 s67, 29
	s_cbranch_scc0 .LBB0_281
	s_and_b64 vcc, exec, s[4:5]
	s_cbranch_vccnz .LBB0_286
	s_cmp_lt_i32 s57, 30
	s_mov_b64 s[18:19], -1
	s_cbranch_scc1 .LBB0_287
